# GEMM K-loops: removed the lgkmcnt(0) repeated after each phase barrier and the adjacent s_setprio 0/1 pairs
# baseline (speedup 1.0000x reference)
.LBB0_213:
	s_mov_b32 s14, 0xfffc0080
	s_cmp_eq_u32 s7, 12
	s_mov_b32 s15, -1
	v_lshl_add_u64 v[144:145], v[142:143], 0, s[14:15]
	s_cselect_b64 vcc, -1, 0
	s_add_i32 s9, 0, 0x10000
	s_add_i32 s14, 0, 0x14000
	v_add_u32_e32 v162, s9, v148
	v_add_u32_e32 v178, s14, v148
	ds_read_b128 v[150:153], v162
	ds_read_b128 v[154:157], v162 offset:1024
	ds_read_b128 v[158:161], v162 offset:2048
	ds_read_b128 v[162:165], v162 offset:3072
	ds_read_b128 v[166:169], v178
	ds_read_b128 v[170:173], v178 offset:1024
	ds_read_b128 v[174:177], v178 offset:2048
	ds_read_b128 v[178:181], v178 offset:3072
	v_cndmask_b32_e32 v145, v145, v137, vcc
	v_cndmask_b32_e32 v144, v144, v136, vcc
	v_cndmask_b32_e32 v183, v141, v139, vcc
	v_cndmask_b32_e32 v182, v140, v138, vcc
	v_lshl_add_u64 v[184:185], v[142:143], 0, v[134:135]
	s_add_i32 m0, s41, 0xc000
	ds_read_b128 v[196:199], v149
	ds_read_b128 v[200:203], v149 offset:1024
	ds_read_b128 v[204:207], v149 offset:2048
	ds_read_b128 v[208:211], v149 offset:3072
	ds_read_b128 v[212:215], v149 offset:4096
	ds_read_b128 v[216:219], v149 offset:5120
	ds_read_b128 v[220:223], v149 offset:6144
	ds_read_b128 v[224:227], v149 offset:7168
	global_load_lds_dwordx4 v[184:185], off
	v_lshl_add_u64 v[184:185], v[142:143], 0, v[132:133]
	s_add_i32 m0, s41, 0xe000
	s_nop 0
	global_load_lds_dwordx4 v[184:185], off
	s_waitcnt vmcnt(8)
	s_waitcnt lgkmcnt(0)
	s_barrier
	s_setprio 1
	v_mfma_f32_16x16x32_bf16 v[128:131], v[150:153], v[196:199], v[128:131]
	v_mfma_f32_16x16x32_bf16 v[124:127], v[158:161], v[196:199], v[124:127]
	v_mfma_f32_16x16x32_bf16 v[112:115], v[150:153], v[204:207], v[112:115]
	v_mfma_f32_16x16x32_bf16 v[108:111], v[158:161], v[204:207], v[108:111]
	v_mfma_f32_16x16x32_bf16 v[96:99], v[150:153], v[212:215], v[96:99]
	v_mfma_f32_16x16x32_bf16 v[92:95], v[158:161], v[212:215], v[92:95]
	v_mfma_f32_16x16x32_bf16 v[80:83], v[150:153], v[220:223], v[80:83]
	v_mfma_f32_16x16x32_bf16 v[76:79], v[158:161], v[220:223], v[76:79]
	v_mfma_f32_16x16x32_bf16 v[128:131], v[154:157], v[200:203], v[128:131]
	v_mfma_f32_16x16x32_bf16 v[124:127], v[162:165], v[200:203], v[124:127]
	v_mfma_f32_16x16x32_bf16 v[112:115], v[154:157], v[208:211], v[112:115]
	v_mfma_f32_16x16x32_bf16 v[108:111], v[162:165], v[208:211], v[108:111]
	v_mfma_f32_16x16x32_bf16 v[96:99], v[154:157], v[216:219], v[96:99]
	v_mfma_f32_16x16x32_bf16 v[92:95], v[162:165], v[216:219], v[92:95]
	v_mfma_f32_16x16x32_bf16 v[80:83], v[154:157], v[224:227], v[80:83]
	v_mfma_f32_16x16x32_bf16 v[76:79], v[162:165], v[224:227], v[76:79]
	v_mfma_f32_16x16x32_bf16 v[120:123], v[166:169], v[196:199], v[120:123]
	v_mfma_f32_16x16x32_bf16 v[116:119], v[174:177], v[196:199], v[116:119]
	v_mfma_f32_16x16x32_bf16 v[104:107], v[166:169], v[204:207], v[104:107]
	v_mfma_f32_16x16x32_bf16 v[100:103], v[174:177], v[204:207], v[100:103]
	v_mfma_f32_16x16x32_bf16 v[88:91], v[166:169], v[212:215], v[88:91]
	v_mfma_f32_16x16x32_bf16 v[84:87], v[174:177], v[212:215], v[84:87]
	v_mfma_f32_16x16x32_bf16 v[72:75], v[166:169], v[220:223], v[72:75]
	v_mfma_f32_16x16x32_bf16 v[68:71], v[174:177], v[220:223], v[68:71]
	v_mfma_f32_16x16x32_bf16 v[120:123], v[170:173], v[200:203], v[120:123]
	v_mfma_f32_16x16x32_bf16 v[116:119], v[178:181], v[200:203], v[116:119]
	v_mfma_f32_16x16x32_bf16 v[104:107], v[170:173], v[208:211], v[104:107]
	v_mfma_f32_16x16x32_bf16 v[100:103], v[178:181], v[208:211], v[100:103]
	v_mfma_f32_16x16x32_bf16 v[88:91], v[170:173], v[216:219], v[88:91]
	v_mfma_f32_16x16x32_bf16 v[84:87], v[178:181], v[216:219], v[84:87]
	v_mfma_f32_16x16x32_bf16 v[72:75], v[170:173], v[224:227], v[72:75]
	v_mfma_f32_16x16x32_bf16 v[68:71], v[178:181], v[224:227], v[68:71]
	s_setprio 0
	s_barrier
	s_add_i32 s9, s9, s34
	v_lshl_add_u64 v[184:185], v[182:183], 0, v[2:3]
	s_mov_b32 m0, s9
	ds_read_b128 v[196:199], v149 offset:16384
	ds_read_b128 v[200:203], v149 offset:17408
	ds_read_b128 v[204:207], v149 offset:18432
	ds_read_b128 v[208:211], v149 offset:19456
	ds_read_b128 v[212:215], v149 offset:20480
	ds_read_b128 v[216:219], v149 offset:21504
	ds_read_b128 v[220:223], v149 offset:22528
	ds_read_b128 v[224:227], v149 offset:23552
	global_load_lds_dwordx4 v[184:185], off
	v_lshl_add_u64 v[186:187], v[182:183], 0, v[0:1]
	s_add_i32 m0, s9, 0x2000
	v_lshl_add_u64 v[192:193], v[182:183], 0, s[62:63]
	s_add_i32 s9, s14, s34
	global_load_lds_dwordx4 v[186:187], off
	v_lshl_add_u64 v[194:195], v[192:193], 0, v[2:3]
	s_mov_b32 m0, s9
	v_lshl_add_u64 v[192:193], v[192:193], 0, v[0:1]
	global_load_lds_dwordx4 v[194:195], off
	s_add_i32 m0, s9, 0x2000
	v_lshl_add_u64 v[194:195], v[144:145], 0, v[0:1]
	global_load_lds_dwordx4 v[192:193], off
	v_lshl_add_u64 v[192:193], v[144:145], 0, v[2:3]
	s_mov_b32 m0, s41
	s_nop 0
	global_load_lds_dwordx4 v[192:193], off
	s_mov_b32 m0, s42
	s_nop 0
	global_load_lds_dwordx4 v[194:195], off
	s_waitcnt vmcnt(8)
	s_waitcnt lgkmcnt(0)
	s_barrier
	s_setprio 1
	v_mfma_f32_16x16x32_bf16 v[64:67], v[150:153], v[196:199], v[64:67]
	v_mfma_f32_16x16x32_bf16 v[60:63], v[158:161], v[196:199], v[60:63]
	v_mfma_f32_16x16x32_bf16 v[48:51], v[150:153], v[204:207], v[48:51]
	v_mfma_f32_16x16x32_bf16 v[44:47], v[158:161], v[204:207], v[44:47]
	v_mfma_f32_16x16x32_bf16 v[32:35], v[150:153], v[212:215], v[32:35]
	v_mfma_f32_16x16x32_bf16 v[28:31], v[158:161], v[212:215], v[28:31]
	v_mfma_f32_16x16x32_bf16 v[16:19], v[150:153], v[220:223], v[16:19]
	v_mfma_f32_16x16x32_bf16 v[12:15], v[158:161], v[220:223], v[12:15]
	v_mfma_f32_16x16x32_bf16 v[64:67], v[154:157], v[200:203], v[64:67]
	v_mfma_f32_16x16x32_bf16 v[60:63], v[162:165], v[200:203], v[60:63]
	v_mfma_f32_16x16x32_bf16 v[48:51], v[154:157], v[208:211], v[48:51]
	v_mfma_f32_16x16x32_bf16 v[44:47], v[162:165], v[208:211], v[44:47]
	v_mfma_f32_16x16x32_bf16 v[32:35], v[154:157], v[216:219], v[32:35]
	v_mfma_f32_16x16x32_bf16 v[28:31], v[162:165], v[216:219], v[28:31]
	v_mfma_f32_16x16x32_bf16 v[16:19], v[154:157], v[224:227], v[16:19]
	v_mfma_f32_16x16x32_bf16 v[12:15], v[162:165], v[224:227], v[12:15]
	v_mfma_f32_16x16x32_bf16 v[56:59], v[166:169], v[196:199], v[56:59]
	v_mfma_f32_16x16x32_bf16 v[52:55], v[174:177], v[196:199], v[52:55]
	v_mfma_f32_16x16x32_bf16 v[40:43], v[166:169], v[204:207], v[40:43]
	v_mfma_f32_16x16x32_bf16 v[36:39], v[174:177], v[204:207], v[36:39]
	v_mfma_f32_16x16x32_bf16 v[24:27], v[166:169], v[212:215], v[24:27]
	v_mfma_f32_16x16x32_bf16 v[20:23], v[174:177], v[212:215], v[20:23]
	v_mfma_f32_16x16x32_bf16 v[8:11], v[166:169], v[220:223], v[8:11]
	v_mfma_f32_16x16x32_bf16 v[4:7], v[174:177], v[220:223], v[4:7]
	v_mfma_f32_16x16x32_bf16 v[56:59], v[170:173], v[200:203], v[56:59]
	v_mfma_f32_16x16x32_bf16 v[52:55], v[178:181], v[200:203], v[52:55]
	v_mfma_f32_16x16x32_bf16 v[40:43], v[170:173], v[208:211], v[40:43]
	v_mfma_f32_16x16x32_bf16 v[36:39], v[178:181], v[208:211], v[36:39]
	v_mfma_f32_16x16x32_bf16 v[24:27], v[170:173], v[216:219], v[24:27]
	v_mfma_f32_16x16x32_bf16 v[20:23], v[178:181], v[216:219], v[20:23]
	v_mfma_f32_16x16x32_bf16 v[8:11], v[170:173], v[224:227], v[8:11]
	v_mfma_f32_16x16x32_bf16 v[4:7], v[178:181], v[224:227], v[4:7]
	s_setprio 0
	s_barrier
	s_add_i32 s9, 0, 0x18000
	s_add_i32 s14, 0, 0x1c000
	v_add_u32_e32 v162, s9, v148
	v_add_u32_e32 v178, s14, v148
	ds_read_b128 v[150:153], v162
	ds_read_b128 v[154:157], v162 offset:1024
	ds_read_b128 v[158:161], v162 offset:2048
	ds_read_b128 v[162:165], v162 offset:3072
	ds_read_b128 v[166:169], v178
	ds_read_b128 v[170:173], v178 offset:1024
	ds_read_b128 v[174:177], v178 offset:2048
	ds_read_b128 v[178:181], v178 offset:3072
	v_lshl_add_u64 v[144:145], v[144:145], 0, s[62:63]
	s_mov_b32 m0, s43
	v_lshl_add_u64 v[228:229], v[144:145], 0, v[2:3]
	ds_read_b128 v[196:199], v149 offset:32768
	ds_read_b128 v[200:203], v149 offset:33792
	ds_read_b128 v[204:207], v149 offset:34816
	ds_read_b128 v[208:211], v149 offset:35840
	ds_read_b128 v[212:215], v149 offset:36864
	ds_read_b128 v[216:219], v149 offset:37888
	ds_read_b128 v[220:223], v149 offset:38912
	ds_read_b128 v[224:227], v149 offset:39936
	global_load_lds_dwordx4 v[228:229], off
	v_lshl_add_u64 v[144:145], v[144:145], 0, v[0:1]
	s_mov_b32 m0, s44
	s_nop 0
	global_load_lds_dwordx4 v[144:145], off
	s_waitcnt vmcnt(8)
	s_waitcnt lgkmcnt(0)
	s_barrier
	s_setprio 1
	v_mfma_f32_16x16x32_bf16 v[128:131], v[150:153], v[196:199], v[128:131]
	v_mfma_f32_16x16x32_bf16 v[124:127], v[158:161], v[196:199], v[124:127]
	v_mfma_f32_16x16x32_bf16 v[112:115], v[150:153], v[204:207], v[112:115]
	v_mfma_f32_16x16x32_bf16 v[108:111], v[158:161], v[204:207], v[108:111]
	v_mfma_f32_16x16x32_bf16 v[96:99], v[150:153], v[212:215], v[96:99]
	v_mfma_f32_16x16x32_bf16 v[92:95], v[158:161], v[212:215], v[92:95]
	v_mfma_f32_16x16x32_bf16 v[80:83], v[150:153], v[220:223], v[80:83]
	v_mfma_f32_16x16x32_bf16 v[76:79], v[158:161], v[220:223], v[76:79]
	v_mfma_f32_16x16x32_bf16 v[128:131], v[154:157], v[200:203], v[128:131]
	v_mfma_f32_16x16x32_bf16 v[124:127], v[162:165], v[200:203], v[124:127]
	v_mfma_f32_16x16x32_bf16 v[112:115], v[154:157], v[208:211], v[112:115]
	v_mfma_f32_16x16x32_bf16 v[108:111], v[162:165], v[208:211], v[108:111]
	v_mfma_f32_16x16x32_bf16 v[96:99], v[154:157], v[216:219], v[96:99]
	v_mfma_f32_16x16x32_bf16 v[92:95], v[162:165], v[216:219], v[92:95]
	v_mfma_f32_16x16x32_bf16 v[80:83], v[154:157], v[224:227], v[80:83]
	v_mfma_f32_16x16x32_bf16 v[76:79], v[162:165], v[224:227], v[76:79]
	v_mfma_f32_16x16x32_bf16 v[120:123], v[166:169], v[196:199], v[120:123]
	v_mfma_f32_16x16x32_bf16 v[116:119], v[174:177], v[196:199], v[116:119]
	v_mfma_f32_16x16x32_bf16 v[104:107], v[166:169], v[204:207], v[104:107]
	v_mfma_f32_16x16x32_bf16 v[100:103], v[174:177], v[204:207], v[100:103]
	v_mfma_f32_16x16x32_bf16 v[88:91], v[166:169], v[212:215], v[88:91]
	v_mfma_f32_16x16x32_bf16 v[84:87], v[174:177], v[212:215], v[84:87]
	v_mfma_f32_16x16x32_bf16 v[72:75], v[166:169], v[220:223], v[72:75]
	v_mfma_f32_16x16x32_bf16 v[68:71], v[174:177], v[220:223], v[68:71]
	v_mfma_f32_16x16x32_bf16 v[120:123], v[170:173], v[200:203], v[120:123]
	v_mfma_f32_16x16x32_bf16 v[116:119], v[178:181], v[200:203], v[116:119]
	v_mfma_f32_16x16x32_bf16 v[104:107], v[170:173], v[208:211], v[104:107]
	v_mfma_f32_16x16x32_bf16 v[100:103], v[178:181], v[208:211], v[100:103]
	v_mfma_f32_16x16x32_bf16 v[88:91], v[170:173], v[216:219], v[88:91]
	v_mfma_f32_16x16x32_bf16 v[84:87], v[178:181], v[216:219], v[84:87]
	v_mfma_f32_16x16x32_bf16 v[72:75], v[170:173], v[224:227], v[72:75]
	v_mfma_f32_16x16x32_bf16 v[68:71], v[178:181], v[224:227], v[68:71]
	s_setprio 0
	s_barrier
	s_add_i32 s9, s9, s34
	v_lshl_add_u64 v[144:145], v[184:185], 0, s[46:47]
	s_mov_b32 m0, s9
	ds_read_b128 v[196:199], v149 offset:49152
	ds_read_b128 v[200:203], v149 offset:50176
	ds_read_b128 v[204:207], v149 offset:51200
	ds_read_b128 v[208:211], v149 offset:52224
	ds_read_b128 v[212:215], v149 offset:53248
	ds_read_b128 v[216:219], v149 offset:54272
	ds_read_b128 v[220:223], v149 offset:55296
	ds_read_b128 v[224:227], v149 offset:56320
	global_load_lds_dwordx4 v[144:145], off
	v_lshl_add_u64 v[144:145], v[186:187], 0, s[46:47]
	s_add_i32 m0, s9, 0x2000
	s_add_i32 s9, s14, s34
	global_load_lds_dwordx4 v[144:145], off
	v_lshl_add_u64 v[144:145], v[182:183], 0, s[72:73]
	v_lshl_add_u64 v[182:183], v[144:145], 0, v[2:3]
	s_mov_b32 m0, s9
	v_lshl_add_u64 v[144:145], v[144:145], 0, v[0:1]
	global_load_lds_dwordx4 v[182:183], off
	s_add_i32 m0, s9, 0x2000
	s_nop 0
	global_load_lds_dwordx4 v[144:145], off
	v_lshl_add_u64 v[144:145], v[192:193], 0, s[46:47]
	s_mov_b32 m0, s45
	s_nop 0
	global_load_lds_dwordx4 v[144:145], off
	v_lshl_add_u64 v[144:145], v[194:195], 0, s[46:47]
	s_mov_b32 m0, s48
	s_nop 0
	global_load_lds_dwordx4 v[144:145], off
	s_waitcnt vmcnt(8)
	s_waitcnt lgkmcnt(0)
	s_barrier
	s_setprio 1
	v_mfma_f32_16x16x32_bf16 v[64:67], v[150:153], v[196:199], v[64:67]
	v_mfma_f32_16x16x32_bf16 v[60:63], v[158:161], v[196:199], v[60:63]
	v_mfma_f32_16x16x32_bf16 v[48:51], v[150:153], v[204:207], v[48:51]
	v_mfma_f32_16x16x32_bf16 v[44:47], v[158:161], v[204:207], v[44:47]
	v_mfma_f32_16x16x32_bf16 v[32:35], v[150:153], v[212:215], v[32:35]
	v_mfma_f32_16x16x32_bf16 v[28:31], v[158:161], v[212:215], v[28:31]
	v_mfma_f32_16x16x32_bf16 v[16:19], v[150:153], v[220:223], v[16:19]
	v_mfma_f32_16x16x32_bf16 v[12:15], v[158:161], v[220:223], v[12:15]
	v_mfma_f32_16x16x32_bf16 v[64:67], v[154:157], v[200:203], v[64:67]
	v_mfma_f32_16x16x32_bf16 v[60:63], v[162:165], v[200:203], v[60:63]
	v_mfma_f32_16x16x32_bf16 v[48:51], v[154:157], v[208:211], v[48:51]
	v_mfma_f32_16x16x32_bf16 v[44:47], v[162:165], v[208:211], v[44:47]
	v_mfma_f32_16x16x32_bf16 v[32:35], v[154:157], v[216:219], v[32:35]
	v_mfma_f32_16x16x32_bf16 v[28:31], v[162:165], v[216:219], v[28:31]
	v_mfma_f32_16x16x32_bf16 v[16:19], v[154:157], v[224:227], v[16:19]
	v_mfma_f32_16x16x32_bf16 v[12:15], v[162:165], v[224:227], v[12:15]
	v_mfma_f32_16x16x32_bf16 v[56:59], v[166:169], v[196:199], v[56:59]
	v_mfma_f32_16x16x32_bf16 v[52:55], v[174:177], v[196:199], v[52:55]
	v_mfma_f32_16x16x32_bf16 v[40:43], v[166:169], v[204:207], v[40:43]
	v_mfma_f32_16x16x32_bf16 v[36:39], v[174:177], v[204:207], v[36:39]
	v_mfma_f32_16x16x32_bf16 v[24:27], v[166:169], v[212:215], v[24:27]
	v_mfma_f32_16x16x32_bf16 v[20:23], v[174:177], v[212:215], v[20:23]
	v_mfma_f32_16x16x32_bf16 v[8:11], v[166:169], v[220:223], v[8:11]
	v_mfma_f32_16x16x32_bf16 v[4:7], v[174:177], v[220:223], v[4:7]
	v_mfma_f32_16x16x32_bf16 v[56:59], v[170:173], v[200:203], v[56:59]
	v_mfma_f32_16x16x32_bf16 v[52:55], v[178:181], v[200:203], v[52:55]
	v_mfma_f32_16x16x32_bf16 v[40:43], v[170:173], v[208:211], v[40:43]
	v_mfma_f32_16x16x32_bf16 v[36:39], v[178:181], v[208:211], v[36:39]
	v_mfma_f32_16x16x32_bf16 v[24:27], v[170:173], v[216:219], v[24:27]
	v_mfma_f32_16x16x32_bf16 v[20:23], v[178:181], v[216:219], v[20:23]
	v_mfma_f32_16x16x32_bf16 v[8:11], v[170:173], v[224:227], v[8:11]
	v_mfma_f32_16x16x32_bf16 v[4:7], v[178:181], v[224:227], v[4:7]
	s_setprio 0
	s_barrier
	s_add_i32 s7, s7, 2
	v_lshl_add_u64 v[140:141], v[140:141], 0, s[74:75]
	s_cmp_gt_u32 s7, 13
	v_lshl_add_u64 v[142:143], v[142:143], 0, s[74:75]
	s_cbranch_scc0 .LBB0_213
	s_and_b64 vcc, exec, s[12:13]
	s_cbranch_vccz .LBB0_216
	s_barrier

.LBB0_370:
	s_add_u32 s8, s6, 0xfffc0080
	s_addc_u32 s9, s7, -1
	s_add_i32 s26, 0, 0x10000
	s_cmp_eq_u32 s21, 12
	s_cselect_b32 s11, s1, s9
	s_cselect_b32 s10, s3, s8
	v_add_u32_e32 v2, s26, v244
	s_cselect_b32 s9, s12, s15
	s_cselect_b32 s8, s13, s14
	s_add_i32 s28, 0, 0x14000
	ds_read_b128 v[96:99], v2
	ds_read_b128 v[100:103], v2 offset:1024
	ds_read_b128 v[104:107], v2 offset:2048
	ds_read_b128 v[144:147], v2 offset:3072
	v_add_u32_e32 v2, s28, v244
	ds_read_b128 v[148:151], v2
	ds_read_b128 v[152:155], v2 offset:1024
	ds_read_b128 v[156:159], v2 offset:2048
	ds_read_b128 v[160:163], v2 offset:3072
	v_lshl_add_u64 v[184:185], s[6:7], 0, v[202:203]
	s_add_i32 m0, s73, 0xc000
	ds_read_b128 v[164:167], v245
	ds_read_b128 v[168:171], v245 offset:1024
	ds_read_b128 v[172:175], v245 offset:2048
	ds_read_b128 v[176:179], v245 offset:3072
	ds_read_b128 v[180:183], v245 offset:4096
	ds_read_b128 v[206:209], v245 offset:5120
	ds_read_b128 v[210:213], v245 offset:6144
	ds_read_b128 v[214:217], v245 offset:7168
	global_load_lds_dwordx4 v[184:185], off
	v_lshl_add_u64 v[184:185], s[6:7], 0, v[204:205]
	s_add_i32 m0, s73, 0xe000
	s_nop 0
	global_load_lds_dwordx4 v[184:185], off
	s_waitcnt vmcnt(8)
	s_waitcnt lgkmcnt(0)
	s_barrier
	s_setprio 1
	v_mfma_f32_16x16x32_bf16 v[140:143], v[96:99], v[164:167], v[140:143]
	v_mfma_f32_16x16x32_bf16 v[92:95], v[104:107], v[164:167], v[92:95]
	v_mfma_f32_16x16x32_bf16 v[136:139], v[96:99], v[172:175], v[136:139]
	v_mfma_f32_16x16x32_bf16 v[88:91], v[104:107], v[172:175], v[88:91]
	v_mfma_f32_16x16x32_bf16 v[132:135], v[96:99], v[180:183], v[132:135]
	v_mfma_f32_16x16x32_bf16 v[84:87], v[104:107], v[180:183], v[84:87]
	v_mfma_f32_16x16x32_bf16 v[108:111], v[96:99], v[210:213], v[108:111]
	v_mfma_f32_16x16x32_bf16 v[112:115], v[104:107], v[210:213], v[112:115]
	v_mfma_f32_16x16x32_bf16 v[140:143], v[100:103], v[168:171], v[140:143]
	v_mfma_f32_16x16x32_bf16 v[92:95], v[144:147], v[168:171], v[92:95]
	v_mfma_f32_16x16x32_bf16 v[136:139], v[100:103], v[176:179], v[136:139]
	v_mfma_f32_16x16x32_bf16 v[88:91], v[144:147], v[176:179], v[88:91]
	v_mfma_f32_16x16x32_bf16 v[132:135], v[100:103], v[206:209], v[132:135]
	v_mfma_f32_16x16x32_bf16 v[84:87], v[144:147], v[206:209], v[84:87]
	v_mfma_f32_16x16x32_bf16 v[108:111], v[100:103], v[214:217], v[108:111]
	v_mfma_f32_16x16x32_bf16 v[112:115], v[144:147], v[214:217], v[112:115]
	v_mfma_f32_16x16x32_bf16 v[128:131], v[148:151], v[164:167], v[128:131]
	v_mfma_f32_16x16x32_bf16 v[80:83], v[156:159], v[164:167], v[80:83]
	v_mfma_f32_16x16x32_bf16 v[124:127], v[148:151], v[172:175], v[124:127]
	v_mfma_f32_16x16x32_bf16 v[76:79], v[156:159], v[172:175], v[76:79]
	v_mfma_f32_16x16x32_bf16 v[120:123], v[148:151], v[180:183], v[120:123]
	v_mfma_f32_16x16x32_bf16 v[72:75], v[156:159], v[180:183], v[72:75]
	v_mfma_f32_16x16x32_bf16 v[116:119], v[148:151], v[210:213], v[116:119]
	v_mfma_f32_16x16x32_bf16 v[68:71], v[156:159], v[210:213], v[68:71]
	v_mfma_f32_16x16x32_bf16 v[128:131], v[152:155], v[168:171], v[128:131]
	v_mfma_f32_16x16x32_bf16 v[80:83], v[160:163], v[168:171], v[80:83]
	v_mfma_f32_16x16x32_bf16 v[124:127], v[152:155], v[176:179], v[124:127]
	v_mfma_f32_16x16x32_bf16 v[76:79], v[160:163], v[176:179], v[76:79]
	v_mfma_f32_16x16x32_bf16 v[120:123], v[152:155], v[206:209], v[120:123]
	v_mfma_f32_16x16x32_bf16 v[72:75], v[160:163], v[206:209], v[72:75]
	v_mfma_f32_16x16x32_bf16 v[116:119], v[152:155], v[214:217], v[116:119]
	v_mfma_f32_16x16x32_bf16 v[68:71], v[160:163], v[214:217], v[68:71]
	s_setprio 0
	s_barrier
	s_add_i32 s26, s26, s72
	v_lshl_add_u64 v[184:185], s[8:9], 0, v[196:197]
	s_mov_b32 m0, s26
	ds_read_b128 v[164:167], v245 offset:16384
	ds_read_b128 v[168:171], v245 offset:17408
	ds_read_b128 v[172:175], v245 offset:18432
	ds_read_b128 v[176:179], v245 offset:19456
	ds_read_b128 v[180:183], v245 offset:20480
	ds_read_b128 v[206:209], v245 offset:21504
	ds_read_b128 v[210:213], v245 offset:22528
	ds_read_b128 v[214:217], v245 offset:23552
	global_load_lds_dwordx4 v[184:185], off
	s_add_i32 m0, s26, 0x2000
	s_add_u32 s26, s8, 0x40000
	v_lshl_add_u64 v[186:187], s[8:9], 0, v[200:201]
	s_addc_u32 s27, s9, 0
	s_add_i32 s28, s28, s72
	global_load_lds_dwordx4 v[186:187], off
	v_lshl_add_u64 v[192:193], s[26:27], 0, v[196:197]
	s_mov_b32 m0, s28
	v_lshl_add_u64 v[194:195], s[10:11], 0, v[198:199]
	global_load_lds_dwordx4 v[192:193], off
	v_lshl_add_u64 v[192:193], s[26:27], 0, v[200:201]
	s_add_i32 m0, s28, 0x2000
	s_nop 0
	global_load_lds_dwordx4 v[192:193], off
	v_lshl_add_u64 v[192:193], s[10:11], 0, v[0:1]
	s_mov_b32 m0, s73
	s_nop 0
	global_load_lds_dwordx4 v[192:193], off
	s_mov_b32 m0, s74
	s_nop 0
	global_load_lds_dwordx4 v[194:195], off
	s_waitcnt vmcnt(8)
	s_waitcnt lgkmcnt(0)
	s_barrier
	s_setprio 1
	v_mfma_f32_16x16x32_bf16 v[64:67], v[96:99], v[164:167], v[64:67]
	v_mfma_f32_16x16x32_bf16 v[28:31], v[104:107], v[164:167], v[28:31]
	v_mfma_f32_16x16x32_bf16 v[60:63], v[96:99], v[172:175], v[60:63]
	v_mfma_f32_16x16x32_bf16 v[24:27], v[104:107], v[172:175], v[24:27]
	v_mfma_f32_16x16x32_bf16 v[56:59], v[96:99], v[180:183], v[56:59]
	v_mfma_f32_16x16x32_bf16 v[20:23], v[104:107], v[180:183], v[20:23]
	v_mfma_f32_16x16x32_bf16 v[32:35], v[96:99], v[210:213], v[32:35]
	v_mfma_f32_16x16x32_bf16 v[36:39], v[104:107], v[210:213], v[36:39]
	v_mfma_f32_16x16x32_bf16 v[64:67], v[100:103], v[168:171], v[64:67]
	v_mfma_f32_16x16x32_bf16 v[28:31], v[144:147], v[168:171], v[28:31]
	v_mfma_f32_16x16x32_bf16 v[60:63], v[100:103], v[176:179], v[60:63]
	v_mfma_f32_16x16x32_bf16 v[24:27], v[144:147], v[176:179], v[24:27]
	v_mfma_f32_16x16x32_bf16 v[56:59], v[100:103], v[206:209], v[56:59]
	v_mfma_f32_16x16x32_bf16 v[20:23], v[144:147], v[206:209], v[20:23]
	v_mfma_f32_16x16x32_bf16 v[32:35], v[100:103], v[214:217], v[32:35]
	v_mfma_f32_16x16x32_bf16 v[36:39], v[144:147], v[214:217], v[36:39]
	v_mfma_f32_16x16x32_bf16 v[52:55], v[148:151], v[164:167], v[52:55]
	v_mfma_f32_16x16x32_bf16 v[16:19], v[156:159], v[164:167], v[16:19]
	v_mfma_f32_16x16x32_bf16 v[48:51], v[148:151], v[172:175], v[48:51]
	v_mfma_f32_16x16x32_bf16 v[12:15], v[156:159], v[172:175], v[12:15]
	v_mfma_f32_16x16x32_bf16 v[44:47], v[148:151], v[180:183], v[44:47]
	v_mfma_f32_16x16x32_bf16 v[8:11], v[156:159], v[180:183], v[8:11]
	v_mfma_f32_16x16x32_bf16 v[40:43], v[148:151], v[210:213], v[40:43]
	v_mfma_f32_16x16x32_bf16 v[4:7], v[156:159], v[210:213], v[4:7]
	v_mfma_f32_16x16x32_bf16 v[52:55], v[152:155], v[168:171], v[52:55]
	v_mfma_f32_16x16x32_bf16 v[16:19], v[160:163], v[168:171], v[16:19]
	v_mfma_f32_16x16x32_bf16 v[48:51], v[152:155], v[176:179], v[48:51]
	v_mfma_f32_16x16x32_bf16 v[12:15], v[160:163], v[176:179], v[12:15]
	v_mfma_f32_16x16x32_bf16 v[44:47], v[152:155], v[206:209], v[44:47]
	v_mfma_f32_16x16x32_bf16 v[8:11], v[160:163], v[206:209], v[8:11]
	v_mfma_f32_16x16x32_bf16 v[40:43], v[152:155], v[214:217], v[40:43]
	v_mfma_f32_16x16x32_bf16 v[4:7], v[160:163], v[214:217], v[4:7]
	s_setprio 0
	s_barrier
	s_add_i32 s26, 0, 0x18000
	v_add_u32_e32 v2, s26, v244
	s_add_i32 s27, 0, 0x1c000
	ds_read_b128 v[96:99], v2
	ds_read_b128 v[100:103], v2 offset:1024
	ds_read_b128 v[104:107], v2 offset:2048
	ds_read_b128 v[144:147], v2 offset:3072
	v_add_u32_e32 v2, s27, v244
	ds_read_b128 v[148:151], v2
	ds_read_b128 v[152:155], v2 offset:1024
	ds_read_b128 v[156:159], v2 offset:2048
	ds_read_b128 v[160:163], v2 offset:3072
	s_add_u32 s10, s10, 0x40000
	s_addc_u32 s11, s11, 0
	s_mov_b32 m0, s75
	v_lshl_add_u64 v[218:219], s[10:11], 0, v[0:1]
	ds_read_b128 v[164:167], v245 offset:32768
	ds_read_b128 v[168:171], v245 offset:33792
	ds_read_b128 v[172:175], v245 offset:34816
	ds_read_b128 v[176:179], v245 offset:35840
	ds_read_b128 v[180:183], v245 offset:36864
	ds_read_b128 v[206:209], v245 offset:37888
	ds_read_b128 v[210:213], v245 offset:38912
	ds_read_b128 v[214:217], v245 offset:39936
	global_load_lds_dwordx4 v[218:219], off
	v_lshl_add_u64 v[218:219], s[10:11], 0, v[198:199]
	s_mov_b32 m0, s58
	s_nop 0
	global_load_lds_dwordx4 v[218:219], off
	s_waitcnt vmcnt(8)
	s_waitcnt lgkmcnt(0)
	s_barrier
	s_setprio 1
	v_mfma_f32_16x16x32_bf16 v[140:143], v[96:99], v[164:167], v[140:143]
	v_mfma_f32_16x16x32_bf16 v[92:95], v[104:107], v[164:167], v[92:95]
	v_mfma_f32_16x16x32_bf16 v[136:139], v[96:99], v[172:175], v[136:139]
	v_mfma_f32_16x16x32_bf16 v[88:91], v[104:107], v[172:175], v[88:91]
	v_mfma_f32_16x16x32_bf16 v[132:135], v[96:99], v[180:183], v[132:135]
	v_mfma_f32_16x16x32_bf16 v[84:87], v[104:107], v[180:183], v[84:87]
	v_mfma_f32_16x16x32_bf16 v[108:111], v[96:99], v[210:213], v[108:111]
	v_mfma_f32_16x16x32_bf16 v[112:115], v[104:107], v[210:213], v[112:115]
	v_mfma_f32_16x16x32_bf16 v[140:143], v[100:103], v[168:171], v[140:143]
	v_mfma_f32_16x16x32_bf16 v[92:95], v[144:147], v[168:171], v[92:95]
	v_mfma_f32_16x16x32_bf16 v[136:139], v[100:103], v[176:179], v[136:139]
	v_mfma_f32_16x16x32_bf16 v[88:91], v[144:147], v[176:179], v[88:91]
	v_mfma_f32_16x16x32_bf16 v[132:135], v[100:103], v[206:209], v[132:135]
	v_mfma_f32_16x16x32_bf16 v[84:87], v[144:147], v[206:209], v[84:87]
	v_mfma_f32_16x16x32_bf16 v[108:111], v[100:103], v[214:217], v[108:111]
	v_mfma_f32_16x16x32_bf16 v[112:115], v[144:147], v[214:217], v[112:115]
	v_mfma_f32_16x16x32_bf16 v[128:131], v[148:151], v[164:167], v[128:131]
	v_mfma_f32_16x16x32_bf16 v[80:83], v[156:159], v[164:167], v[80:83]
	v_mfma_f32_16x16x32_bf16 v[124:127], v[148:151], v[172:175], v[124:127]
	v_mfma_f32_16x16x32_bf16 v[76:79], v[156:159], v[172:175], v[76:79]
	v_mfma_f32_16x16x32_bf16 v[120:123], v[148:151], v[180:183], v[120:123]
	v_mfma_f32_16x16x32_bf16 v[72:75], v[156:159], v[180:183], v[72:75]
	v_mfma_f32_16x16x32_bf16 v[116:119], v[148:151], v[210:213], v[116:119]
	v_mfma_f32_16x16x32_bf16 v[68:71], v[156:159], v[210:213], v[68:71]
	v_mfma_f32_16x16x32_bf16 v[128:131], v[152:155], v[168:171], v[128:131]
	v_mfma_f32_16x16x32_bf16 v[80:83], v[160:163], v[168:171], v[80:83]
	v_mfma_f32_16x16x32_bf16 v[124:127], v[152:155], v[176:179], v[124:127]
	v_mfma_f32_16x16x32_bf16 v[76:79], v[160:163], v[176:179], v[76:79]
	v_mfma_f32_16x16x32_bf16 v[120:123], v[152:155], v[206:209], v[120:123]
	v_mfma_f32_16x16x32_bf16 v[72:75], v[160:163], v[206:209], v[72:75]
	v_mfma_f32_16x16x32_bf16 v[116:119], v[152:155], v[214:217], v[116:119]
	v_mfma_f32_16x16x32_bf16 v[68:71], v[160:163], v[214:217], v[68:71]
	s_setprio 0
	s_barrier
	s_add_i32 s10, s26, s72
	v_lshl_add_u64 v[184:185], v[184:185], 0, s[46:47]
	s_mov_b32 m0, s10
	ds_read_b128 v[164:167], v245 offset:49152
	ds_read_b128 v[168:171], v245 offset:50176
	ds_read_b128 v[172:175], v245 offset:51200
	ds_read_b128 v[176:179], v245 offset:52224
	ds_read_b128 v[180:183], v245 offset:53248
	ds_read_b128 v[206:209], v245 offset:54272
	ds_read_b128 v[210:213], v245 offset:55296
	ds_read_b128 v[214:217], v245 offset:56320
	global_load_lds_dwordx4 v[184:185], off
	s_add_i32 m0, s10, 0x2000
	s_add_u32 s8, s8, 0x40080
	v_lshl_add_u64 v[184:185], v[186:187], 0, s[46:47]
	s_addc_u32 s9, s9, 0
	s_add_i32 s10, s27, s72
	global_load_lds_dwordx4 v[184:185], off
	v_lshl_add_u64 v[184:185], s[8:9], 0, v[196:197]
	s_mov_b32 m0, s10
	s_nop 0
	global_load_lds_dwordx4 v[184:185], off
	v_lshl_add_u64 v[184:185], s[8:9], 0, v[200:201]
	s_add_i32 m0, s10, 0x2000
	s_nop 0
	global_load_lds_dwordx4 v[184:185], off
	v_lshl_add_u64 v[184:185], v[192:193], 0, s[46:47]
	s_mov_b32 m0, s61
	s_nop 0
	global_load_lds_dwordx4 v[184:185], off
	v_lshl_add_u64 v[184:185], v[194:195], 0, s[46:47]
	s_mov_b32 m0, s91
	s_nop 0
	global_load_lds_dwordx4 v[184:185], off
	s_waitcnt vmcnt(8)
	s_waitcnt lgkmcnt(0)
	s_barrier
	s_setprio 1
	v_mfma_f32_16x16x32_bf16 v[64:67], v[96:99], v[164:167], v[64:67]
	v_mfma_f32_16x16x32_bf16 v[28:31], v[104:107], v[164:167], v[28:31]
	v_mfma_f32_16x16x32_bf16 v[60:63], v[96:99], v[172:175], v[60:63]
	v_mfma_f32_16x16x32_bf16 v[24:27], v[104:107], v[172:175], v[24:27]
	v_mfma_f32_16x16x32_bf16 v[56:59], v[96:99], v[180:183], v[56:59]
	v_mfma_f32_16x16x32_bf16 v[20:23], v[104:107], v[180:183], v[20:23]
	v_mfma_f32_16x16x32_bf16 v[32:35], v[96:99], v[210:213], v[32:35]
	v_mfma_f32_16x16x32_bf16 v[36:39], v[104:107], v[210:213], v[36:39]
	v_mfma_f32_16x16x32_bf16 v[64:67], v[100:103], v[168:171], v[64:67]
	v_mfma_f32_16x16x32_bf16 v[28:31], v[144:147], v[168:171], v[28:31]
	v_mfma_f32_16x16x32_bf16 v[60:63], v[100:103], v[176:179], v[60:63]
	v_mfma_f32_16x16x32_bf16 v[24:27], v[144:147], v[176:179], v[24:27]
	v_mfma_f32_16x16x32_bf16 v[56:59], v[100:103], v[206:209], v[56:59]
	v_mfma_f32_16x16x32_bf16 v[20:23], v[144:147], v[206:209], v[20:23]
	v_mfma_f32_16x16x32_bf16 v[32:35], v[100:103], v[214:217], v[32:35]
	v_mfma_f32_16x16x32_bf16 v[36:39], v[144:147], v[214:217], v[36:39]
	v_mfma_f32_16x16x32_bf16 v[52:55], v[148:151], v[164:167], v[52:55]
	v_mfma_f32_16x16x32_bf16 v[16:19], v[156:159], v[164:167], v[16:19]
	v_mfma_f32_16x16x32_bf16 v[48:51], v[148:151], v[172:175], v[48:51]
	v_mfma_f32_16x16x32_bf16 v[12:15], v[156:159], v[172:175], v[12:15]
	v_mfma_f32_16x16x32_bf16 v[44:47], v[148:151], v[180:183], v[44:47]
	v_mfma_f32_16x16x32_bf16 v[8:11], v[156:159], v[180:183], v[8:11]
	v_mfma_f32_16x16x32_bf16 v[40:43], v[148:151], v[210:213], v[40:43]
	v_mfma_f32_16x16x32_bf16 v[4:7], v[156:159], v[210:213], v[4:7]
	v_mfma_f32_16x16x32_bf16 v[52:55], v[152:155], v[168:171], v[52:55]
	v_mfma_f32_16x16x32_bf16 v[16:19], v[160:163], v[168:171], v[16:19]
	v_mfma_f32_16x16x32_bf16 v[48:51], v[152:155], v[176:179], v[48:51]
	v_mfma_f32_16x16x32_bf16 v[12:15], v[160:163], v[176:179], v[12:15]
	v_mfma_f32_16x16x32_bf16 v[44:47], v[152:155], v[206:209], v[44:47]
	v_mfma_f32_16x16x32_bf16 v[8:11], v[160:163], v[206:209], v[8:11]
	v_mfma_f32_16x16x32_bf16 v[40:43], v[152:155], v[214:217], v[40:43]
	v_mfma_f32_16x16x32_bf16 v[4:7], v[160:163], v[214:217], v[4:7]
	s_setprio 0
	s_barrier
	s_add_i32 s21, s21, 2
	s_add_u32 s6, s6, 0x100
	s_addc_u32 s7, s7, 0
	s_add_u32 s14, s14, 0x100
	s_addc_u32 s15, s15, 0
	s_cmp_gt_u32 s21, 13
	s_cbranch_scc0 .LBB0_370
	s_and_b64 vcc, exec, s[78:79]
	s_cbranch_vccz .LBB0_373
	s_barrier

.LBB0_549:
	s_add_i32 s63, 0, 0x10000
	s_add_i32 s24, 0, 0x14000
	v_add_u32_e32 v188, s63, v150
	v_add_u32_e32 v189, s24, v150
	ds_read_b128 v[4:7], v188
	ds_read_b128 v[8:11], v188 offset:1024
	ds_read_b128 v[12:15], v188 offset:2048
	ds_read_b128 v[16:19], v188 offset:3072
	ds_read_b128 v[20:23], v189
	ds_read_b128 v[24:27], v189 offset:1024
	ds_read_b128 v[28:31], v189 offset:2048
	ds_read_b128 v[32:35], v189 offset:3072
	s_add_u32 s8, s28, 0x40080
	s_addc_u32 s9, s29, 0
	s_add_i32 s86, s58, 0xc000
	v_lshl_add_u64 v[68:69], s[8:9], 0, v[0:1]
	s_mov_b32 m0, s86
	ds_read_b128 v[36:39], v151
	ds_read_b128 v[40:43], v151 offset:1024
	ds_read_b128 v[44:47], v151 offset:2048
	ds_read_b128 v[48:51], v151 offset:3072
	ds_read_b128 v[52:55], v151 offset:4096
	ds_read_b128 v[56:59], v151 offset:5120
	ds_read_b128 v[60:63], v151 offset:6144
	ds_read_b128 v[64:67], v151 offset:7168
	global_load_lds_dwordx4 v[68:69], off
	v_lshl_add_u64 v[68:69], s[8:9], 0, v[132:133]
	s_add_i32 s8, s58, 0xe000
	s_mov_b32 m0, s8
	s_nop 0
	global_load_lds_dwordx4 v[68:69], off
	s_waitcnt vmcnt(8)
	s_waitcnt lgkmcnt(0)
	s_barrier
	s_setprio 1
	v_mfma_f32_16x16x32_bf16 v[68:71], v[4:7], v[36:39], 0
	v_mfma_f32_16x16x32_bf16 v[72:75], v[12:15], v[36:39], 0
	v_mfma_f32_16x16x32_bf16 v[76:79], v[4:7], v[44:47], 0
	v_mfma_f32_16x16x32_bf16 v[80:83], v[12:15], v[44:47], 0
	v_mfma_f32_16x16x32_bf16 v[84:87], v[4:7], v[52:55], 0
	v_mfma_f32_16x16x32_bf16 v[88:91], v[12:15], v[52:55], 0
	v_mfma_f32_16x16x32_bf16 v[92:95], v[4:7], v[60:63], 0
	v_mfma_f32_16x16x32_bf16 v[96:99], v[12:15], v[60:63], 0
	v_mfma_f32_16x16x32_bf16 v[68:71], v[8:11], v[40:43], v[68:71]
	v_mfma_f32_16x16x32_bf16 v[72:75], v[16:19], v[40:43], v[72:75]
	v_mfma_f32_16x16x32_bf16 v[76:79], v[8:11], v[48:51], v[76:79]
	v_mfma_f32_16x16x32_bf16 v[80:83], v[16:19], v[48:51], v[80:83]
	v_mfma_f32_16x16x32_bf16 v[84:87], v[8:11], v[56:59], v[84:87]
	v_mfma_f32_16x16x32_bf16 v[88:91], v[16:19], v[56:59], v[88:91]
	v_mfma_f32_16x16x32_bf16 v[92:95], v[8:11], v[64:67], v[92:95]
	v_mfma_f32_16x16x32_bf16 v[96:99], v[16:19], v[64:67], v[96:99]
	v_mfma_f32_16x16x32_bf16 v[100:103], v[20:23], v[36:39], 0
	v_mfma_f32_16x16x32_bf16 v[36:39], v[28:31], v[36:39], 0
	v_mfma_f32_16x16x32_bf16 v[100:103], v[24:27], v[40:43], v[100:103]
	v_mfma_f32_16x16x32_bf16 v[36:39], v[32:35], v[40:43], v[36:39]
	v_mfma_f32_16x16x32_bf16 v[40:43], v[20:23], v[44:47], 0
	v_mfma_f32_16x16x32_bf16 v[44:47], v[28:31], v[44:47], 0
	v_mfma_f32_16x16x32_bf16 v[40:43], v[24:27], v[48:51], v[40:43]
	v_mfma_f32_16x16x32_bf16 v[44:47], v[32:35], v[48:51], v[44:47]
	v_mfma_f32_16x16x32_bf16 v[48:51], v[20:23], v[52:55], 0
	v_mfma_f32_16x16x32_bf16 v[52:55], v[28:31], v[52:55], 0
	v_mfma_f32_16x16x32_bf16 v[48:51], v[24:27], v[56:59], v[48:51]
	v_mfma_f32_16x16x32_bf16 v[52:55], v[32:35], v[56:59], v[52:55]
	v_mfma_f32_16x16x32_bf16 v[56:59], v[20:23], v[60:63], 0
	v_mfma_f32_16x16x32_bf16 v[60:63], v[28:31], v[60:63], 0
	v_mfma_f32_16x16x32_bf16 v[56:59], v[24:27], v[64:67], v[56:59]
	v_mfma_f32_16x16x32_bf16 v[60:63], v[32:35], v[64:67], v[60:63]
	s_setprio 0
	s_barrier
	s_add_i32 s63, s63, s55
	v_lshl_add_u64 v[184:185], s[44:45], 0, v[2:3]
	s_mov_b64 s[10:11], 0x100
	s_add_i32 s9, s63, 0x2000
	v_lshl_add_u64 v[136:137], v[184:185], 0, s[10:11]
	s_mov_b32 m0, s63
	v_lshl_add_u64 v[186:187], s[44:45], 0, v[134:135]
	s_add_u32 vcc_lo, s44, 0x40100
	ds_read_b128 v[64:67], v151 offset:16384
	ds_read_b128 v[104:107], v151 offset:17408
	ds_read_b128 v[108:111], v151 offset:18432
	ds_read_b128 v[112:115], v151 offset:19456
	ds_read_b128 v[116:119], v151 offset:20480
	ds_read_b128 v[120:123], v151 offset:21504
	ds_read_b128 v[124:127], v151 offset:22528
	ds_read_b128 v[128:131], v151 offset:23552
	global_load_lds_dwordx4 v[136:137], off
	v_lshl_add_u64 v[136:137], v[186:187], 0, s[10:11]
	s_mov_b32 m0, s9
	s_addc_u32 vcc_hi, s45, 0
	s_add_i32 s24, s24, s55
	global_load_lds_dwordx4 v[136:137], off
	v_lshl_add_u64 v[136:137], vcc, 0, v[2:3]
	s_mov_b32 m0, s24
	s_add_i32 s62, s24, 0x2000
	global_load_lds_dwordx4 v[136:137], off
	v_lshl_add_u64 v[136:137], vcc, 0, v[134:135]
	s_mov_b32 m0, s62
	v_lshl_add_u64 v[192:193], s[28:29], 0, v[0:1]
	global_load_lds_dwordx4 v[136:137], off
	v_lshl_add_u64 v[136:137], v[192:193], 0, s[10:11]
	s_mov_b32 m0, s58
	v_lshl_add_u64 v[194:195], s[28:29], 0, v[132:133]
	global_load_lds_dwordx4 v[136:137], off
	v_lshl_add_u64 v[136:137], v[194:195], 0, s[10:11]
	s_mov_b32 m0, s59
	s_nop 0
	global_load_lds_dwordx4 v[136:137], off
	s_waitcnt vmcnt(8)
	s_waitcnt lgkmcnt(0)
	s_barrier
	s_setprio 1
	v_mfma_f32_16x16x32_bf16 v[136:139], v[4:7], v[64:67], 0
	v_mfma_f32_16x16x32_bf16 v[144:147], v[4:7], v[108:111], 0
	v_mfma_f32_16x16x32_bf16 v[156:159], v[4:7], v[116:119], 0
	v_mfma_f32_16x16x32_bf16 v[4:7], v[4:7], v[124:127], 0
	v_mfma_f32_16x16x32_bf16 v[136:139], v[8:11], v[104:107], v[136:139]
	v_mfma_f32_16x16x32_bf16 v[144:147], v[8:11], v[112:115], v[144:147]
	v_mfma_f32_16x16x32_bf16 v[156:159], v[8:11], v[120:123], v[156:159]
	v_mfma_f32_16x16x32_bf16 v[4:7], v[8:11], v[128:131], v[4:7]
	v_mfma_f32_16x16x32_bf16 v[8:11], v[12:15], v[124:127], 0
	v_mfma_f32_16x16x32_bf16 v[140:143], v[12:15], v[64:67], 0
	v_mfma_f32_16x16x32_bf16 v[152:155], v[12:15], v[108:111], 0
	v_mfma_f32_16x16x32_bf16 v[160:163], v[12:15], v[116:119], 0
	v_mfma_f32_16x16x32_bf16 v[8:11], v[16:19], v[128:131], v[8:11]
	v_mfma_f32_16x16x32_bf16 v[140:143], v[16:19], v[104:107], v[140:143]
	v_mfma_f32_16x16x32_bf16 v[152:155], v[16:19], v[112:115], v[152:155]
	v_mfma_f32_16x16x32_bf16 v[160:163], v[16:19], v[120:123], v[160:163]
	v_mfma_f32_16x16x32_bf16 v[12:15], v[20:23], v[64:67], 0
	v_mfma_f32_16x16x32_bf16 v[16:19], v[28:31], v[64:67], 0
	v_mfma_f32_16x16x32_bf16 v[12:15], v[24:27], v[104:107], v[12:15]
	v_mfma_f32_16x16x32_bf16 v[16:19], v[32:35], v[104:107], v[16:19]
	v_mfma_f32_16x16x32_bf16 v[64:67], v[20:23], v[108:111], 0
	v_mfma_f32_16x16x32_bf16 v[104:107], v[28:31], v[108:111], 0
	v_mfma_f32_16x16x32_bf16 v[108:111], v[20:23], v[116:119], 0
	v_mfma_f32_16x16x32_bf16 v[20:23], v[20:23], v[124:127], 0
	v_mfma_f32_16x16x32_bf16 v[64:67], v[24:27], v[112:115], v[64:67]
	v_mfma_f32_16x16x32_bf16 v[104:107], v[32:35], v[112:115], v[104:107]
	v_mfma_f32_16x16x32_bf16 v[108:111], v[24:27], v[120:123], v[108:111]
	v_mfma_f32_16x16x32_bf16 v[112:115], v[28:31], v[116:119], 0
	v_mfma_f32_16x16x32_bf16 v[20:23], v[24:27], v[128:131], v[20:23]
	v_mfma_f32_16x16x32_bf16 v[24:27], v[28:31], v[124:127], 0
	v_mfma_f32_16x16x32_bf16 v[112:115], v[32:35], v[120:123], v[112:115]
	v_mfma_f32_16x16x32_bf16 v[24:27], v[32:35], v[128:131], v[24:27]
	s_setprio 0
	s_barrier
	s_add_i32 s87, 0, 0x18000
	s_add_i32 s67, 0, 0x1c000
	v_add_u32_e32 v228, s87, v150
	v_add_u32_e32 v229, s67, v150
	ds_read_b128 v[28:31], v228
	ds_read_b128 v[32:35], v228 offset:1024
	ds_read_b128 v[116:119], v228 offset:2048
	ds_read_b128 v[120:123], v228 offset:3072
	ds_read_b128 v[124:127], v229
	ds_read_b128 v[128:131], v229 offset:1024
	ds_read_b128 v[164:167], v229 offset:2048
	ds_read_b128 v[168:171], v229 offset:3072
	s_add_u32 vcc_lo, s28, 0x40100
	s_addc_u32 vcc_hi, s29, 0
	s_mov_b32 m0, s61
	v_lshl_add_u64 v[216:217], vcc, 0, v[0:1]
	ds_read_b128 v[172:175], v151 offset:32768
	ds_read_b128 v[176:179], v151 offset:33792
	ds_read_b128 v[180:183], v151 offset:34816
	ds_read_b128 v[196:199], v151 offset:35840
	ds_read_b128 v[200:203], v151 offset:36864
	ds_read_b128 v[204:207], v151 offset:37888
	ds_read_b128 v[208:211], v151 offset:38912
	ds_read_b128 v[212:215], v151 offset:39936
	global_load_lds_dwordx4 v[216:217], off
	v_lshl_add_u64 v[216:217], vcc, 0, v[132:133]
	s_mov_b32 m0, s72
	s_nop 0
	global_load_lds_dwordx4 v[216:217], off
	s_waitcnt vmcnt(8)
	s_waitcnt lgkmcnt(0)
	s_barrier
	s_setprio 1
	v_mfma_f32_16x16x32_bf16 v[68:71], v[28:31], v[172:175], v[68:71]
	v_mfma_f32_16x16x32_bf16 v[72:75], v[116:119], v[172:175], v[72:75]
	v_mfma_f32_16x16x32_bf16 v[76:79], v[28:31], v[180:183], v[76:79]
	v_mfma_f32_16x16x32_bf16 v[80:83], v[116:119], v[180:183], v[80:83]
	v_mfma_f32_16x16x32_bf16 v[84:87], v[28:31], v[200:203], v[84:87]
	v_mfma_f32_16x16x32_bf16 v[88:91], v[116:119], v[200:203], v[88:91]
	v_mfma_f32_16x16x32_bf16 v[92:95], v[28:31], v[208:211], v[92:95]
	v_mfma_f32_16x16x32_bf16 v[96:99], v[116:119], v[208:211], v[96:99]
	v_mfma_f32_16x16x32_bf16 v[68:71], v[32:35], v[176:179], v[68:71]
	v_mfma_f32_16x16x32_bf16 v[72:75], v[120:123], v[176:179], v[72:75]
	v_mfma_f32_16x16x32_bf16 v[76:79], v[32:35], v[196:199], v[76:79]
	v_mfma_f32_16x16x32_bf16 v[80:83], v[120:123], v[196:199], v[80:83]
	v_mfma_f32_16x16x32_bf16 v[84:87], v[32:35], v[204:207], v[84:87]
	v_mfma_f32_16x16x32_bf16 v[88:91], v[120:123], v[204:207], v[88:91]
	v_mfma_f32_16x16x32_bf16 v[92:95], v[32:35], v[212:215], v[92:95]
	v_mfma_f32_16x16x32_bf16 v[96:99], v[120:123], v[212:215], v[96:99]
	v_mfma_f32_16x16x32_bf16 v[100:103], v[124:127], v[172:175], v[100:103]
	v_mfma_f32_16x16x32_bf16 v[36:39], v[164:167], v[172:175], v[36:39]
	v_mfma_f32_16x16x32_bf16 v[40:43], v[124:127], v[180:183], v[40:43]
	v_mfma_f32_16x16x32_bf16 v[44:47], v[164:167], v[180:183], v[44:47]
	v_mfma_f32_16x16x32_bf16 v[48:51], v[124:127], v[200:203], v[48:51]
	v_mfma_f32_16x16x32_bf16 v[52:55], v[164:167], v[200:203], v[52:55]
	v_mfma_f32_16x16x32_bf16 v[56:59], v[124:127], v[208:211], v[56:59]
	v_mfma_f32_16x16x32_bf16 v[60:63], v[164:167], v[208:211], v[60:63]
	v_mfma_f32_16x16x32_bf16 v[100:103], v[128:131], v[176:179], v[100:103]
	v_mfma_f32_16x16x32_bf16 v[36:39], v[168:171], v[176:179], v[36:39]
	v_mfma_f32_16x16x32_bf16 v[40:43], v[128:131], v[196:199], v[40:43]
	v_mfma_f32_16x16x32_bf16 v[44:47], v[168:171], v[196:199], v[44:47]
	v_mfma_f32_16x16x32_bf16 v[48:51], v[128:131], v[204:207], v[48:51]
	v_mfma_f32_16x16x32_bf16 v[52:55], v[168:171], v[204:207], v[52:55]
	v_mfma_f32_16x16x32_bf16 v[56:59], v[128:131], v[212:215], v[56:59]
	v_mfma_f32_16x16x32_bf16 v[60:63], v[168:171], v[212:215], v[60:63]
	s_setprio 0
	s_barrier
	s_add_i32 s87, s87, s55
	s_mov_b64 s[10:11], 0x180
	s_add_i32 s65, s87, 0x2000
	v_lshl_add_u64 v[184:185], v[184:185], 0, s[10:11]
	s_mov_b32 m0, s87
	s_add_u32 vcc_lo, s44, 0x40180
	ds_read_b128 v[172:175], v151 offset:49152
	ds_read_b128 v[176:179], v151 offset:50176
	ds_read_b128 v[180:183], v151 offset:51200
	ds_read_b128 v[196:199], v151 offset:52224
	ds_read_b128 v[200:203], v151 offset:53248
	ds_read_b128 v[204:207], v151 offset:54272
	ds_read_b128 v[208:211], v151 offset:55296
	ds_read_b128 v[212:215], v151 offset:56320
	global_load_lds_dwordx4 v[184:185], off
	v_lshl_add_u64 v[184:185], v[186:187], 0, s[10:11]
	s_mov_b32 m0, s65
	s_addc_u32 vcc_hi, s45, 0
	s_add_i32 s44, s67, s55
	global_load_lds_dwordx4 v[184:185], off
	v_lshl_add_u64 v[184:185], vcc, 0, v[2:3]
	s_mov_b32 m0, s44
	s_add_i32 s45, s44, 0x2000
	global_load_lds_dwordx4 v[184:185], off
	v_lshl_add_u64 v[184:185], vcc, 0, v[134:135]
	s_mov_b32 m0, s45
	s_nop 0
	global_load_lds_dwordx4 v[184:185], off
	v_lshl_add_u64 v[184:185], v[192:193], 0, s[10:11]
	s_mov_b32 m0, s74
	s_nop 0
	global_load_lds_dwordx4 v[184:185], off
	v_lshl_add_u64 v[184:185], v[194:195], 0, s[10:11]
	s_mov_b32 m0, s75
	s_nop 0
	global_load_lds_dwordx4 v[184:185], off
	s_waitcnt vmcnt(8)
	s_waitcnt lgkmcnt(0)
	s_barrier
	s_setprio 1
	v_mfma_f32_16x16x32_bf16 v[4:7], v[28:31], v[208:211], v[4:7]
	v_mfma_f32_16x16x32_bf16 v[8:11], v[116:119], v[208:211], v[8:11]
	v_mfma_f32_16x16x32_bf16 v[136:139], v[28:31], v[172:175], v[136:139]
	v_mfma_f32_16x16x32_bf16 v[140:143], v[116:119], v[172:175], v[140:143]
	v_mfma_f32_16x16x32_bf16 v[144:147], v[28:31], v[180:183], v[144:147]
	v_mfma_f32_16x16x32_bf16 v[152:155], v[116:119], v[180:183], v[152:155]
	v_mfma_f32_16x16x32_bf16 v[156:159], v[28:31], v[200:203], v[156:159]
	v_mfma_f32_16x16x32_bf16 v[160:163], v[116:119], v[200:203], v[160:163]
	v_mfma_f32_16x16x32_bf16 v[4:7], v[32:35], v[212:215], v[4:7]
	v_mfma_f32_16x16x32_bf16 v[8:11], v[120:123], v[212:215], v[8:11]
	v_mfma_f32_16x16x32_bf16 v[136:139], v[32:35], v[176:179], v[136:139]
	v_mfma_f32_16x16x32_bf16 v[140:143], v[120:123], v[176:179], v[140:143]
	v_mfma_f32_16x16x32_bf16 v[144:147], v[32:35], v[196:199], v[144:147]
	v_mfma_f32_16x16x32_bf16 v[152:155], v[120:123], v[196:199], v[152:155]
	v_mfma_f32_16x16x32_bf16 v[156:159], v[32:35], v[204:207], v[156:159]
	v_mfma_f32_16x16x32_bf16 v[160:163], v[120:123], v[204:207], v[160:163]
	v_mfma_f32_16x16x32_bf16 v[12:15], v[124:127], v[172:175], v[12:15]
	v_mfma_f32_16x16x32_bf16 v[16:19], v[164:167], v[172:175], v[16:19]
	v_mfma_f32_16x16x32_bf16 v[28:31], v[124:127], v[180:183], v[64:67]
	v_mfma_f32_16x16x32_bf16 v[32:35], v[164:167], v[180:183], v[104:107]
	v_mfma_f32_16x16x32_bf16 v[64:67], v[124:127], v[200:203], v[108:111]
	v_mfma_f32_16x16x32_bf16 v[104:107], v[164:167], v[200:203], v[112:115]
	v_mfma_f32_16x16x32_bf16 v[20:23], v[124:127], v[208:211], v[20:23]
	v_mfma_f32_16x16x32_bf16 v[24:27], v[164:167], v[208:211], v[24:27]
	v_mfma_f32_16x16x32_bf16 v[12:15], v[128:131], v[176:179], v[12:15]
	v_mfma_f32_16x16x32_bf16 v[16:19], v[168:171], v[176:179], v[16:19]
	v_mfma_f32_16x16x32_bf16 v[28:31], v[128:131], v[196:199], v[28:31]
	v_mfma_f32_16x16x32_bf16 v[32:35], v[168:171], v[196:199], v[32:35]
	v_mfma_f32_16x16x32_bf16 v[64:67], v[128:131], v[204:207], v[64:67]
	v_mfma_f32_16x16x32_bf16 v[104:107], v[168:171], v[204:207], v[104:107]
	v_mfma_f32_16x16x32_bf16 v[20:23], v[128:131], v[212:215], v[20:23]
	v_mfma_f32_16x16x32_bf16 v[24:27], v[168:171], v[212:215], v[24:27]
	s_setprio 0
	s_barrier
	ds_read_b128 v[108:111], v188
	ds_read_b128 v[112:115], v188 offset:1024
	ds_read_b128 v[116:119], v188 offset:2048
	ds_read_b128 v[120:123], v188 offset:3072
	ds_read_b128 v[124:127], v189
	ds_read_b128 v[128:131], v189 offset:1024
	ds_read_b128 v[164:167], v189 offset:2048
	ds_read_b128 v[168:171], v189 offset:3072
	s_add_u32 s28, s28, 0x40180
	s_addc_u32 s29, s29, 0
	s_mov_b32 m0, s86
	v_lshl_add_u64 v[184:185], s[28:29], 0, v[0:1]
	ds_read_b128 v[172:175], v151
	ds_read_b128 v[176:179], v151 offset:1024
	ds_read_b128 v[180:183], v151 offset:2048
	ds_read_b128 v[196:199], v151 offset:3072
	ds_read_b128 v[200:203], v151 offset:4096
	ds_read_b128 v[204:207], v151 offset:5120
	ds_read_b128 v[208:211], v151 offset:6144
	ds_read_b128 v[212:215], v151 offset:7168
	global_load_lds_dwordx4 v[184:185], off
	v_lshl_add_u64 v[184:185], s[28:29], 0, v[132:133]
	s_mov_b32 m0, s8
	s_nop 0
	global_load_lds_dwordx4 v[184:185], off
	s_waitcnt vmcnt(8)
	s_waitcnt lgkmcnt(0)
	s_barrier
	s_setprio 1
	v_mfma_f32_16x16x32_bf16 v[68:71], v[108:111], v[172:175], v[68:71]
	v_mfma_f32_16x16x32_bf16 v[72:75], v[116:119], v[172:175], v[72:75]
	v_mfma_f32_16x16x32_bf16 v[76:79], v[108:111], v[180:183], v[76:79]
	v_mfma_f32_16x16x32_bf16 v[80:83], v[116:119], v[180:183], v[80:83]
	v_mfma_f32_16x16x32_bf16 v[84:87], v[108:111], v[200:203], v[84:87]
	v_mfma_f32_16x16x32_bf16 v[88:91], v[116:119], v[200:203], v[88:91]
	v_mfma_f32_16x16x32_bf16 v[92:95], v[108:111], v[208:211], v[92:95]
	v_mfma_f32_16x16x32_bf16 v[68:71], v[112:115], v[176:179], v[68:71]
	v_mfma_f32_16x16x32_bf16 v[72:75], v[120:123], v[176:179], v[72:75]
	v_mfma_f32_16x16x32_bf16 v[76:79], v[112:115], v[196:199], v[76:79]
	v_mfma_f32_16x16x32_bf16 v[80:83], v[120:123], v[196:199], v[80:83]
	v_mfma_f32_16x16x32_bf16 v[84:87], v[112:115], v[204:207], v[84:87]
	v_mfma_f32_16x16x32_bf16 v[88:91], v[120:123], v[204:207], v[88:91]
	v_mfma_f32_16x16x32_bf16 v[216:219], v[112:115], v[212:215], v[92:95]
	v_mfma_f32_16x16x32_bf16 v[92:95], v[116:119], v[208:211], v[96:99]
	v_mfma_f32_16x16x32_bf16 v[220:223], v[120:123], v[212:215], v[92:95]
	v_mfma_f32_16x16x32_bf16 v[92:95], v[124:127], v[172:175], v[100:103]
	v_mfma_f32_16x16x32_bf16 v[36:39], v[164:167], v[172:175], v[36:39]
	v_mfma_f32_16x16x32_bf16 v[40:43], v[124:127], v[180:183], v[40:43]
	v_mfma_f32_16x16x32_bf16 v[44:47], v[164:167], v[180:183], v[44:47]
	v_mfma_f32_16x16x32_bf16 v[48:51], v[124:127], v[200:203], v[48:51]
	v_mfma_f32_16x16x32_bf16 v[52:55], v[164:167], v[200:203], v[52:55]
	v_mfma_f32_16x16x32_bf16 v[56:59], v[124:127], v[208:211], v[56:59]
	v_mfma_f32_16x16x32_bf16 v[60:63], v[164:167], v[208:211], v[60:63]
	v_mfma_f32_16x16x32_bf16 v[100:103], v[128:131], v[176:179], v[92:95]
	v_mfma_f32_16x16x32_bf16 v[36:39], v[168:171], v[176:179], v[36:39]
	v_mfma_f32_16x16x32_bf16 v[40:43], v[128:131], v[196:199], v[40:43]
	v_mfma_f32_16x16x32_bf16 v[44:47], v[168:171], v[196:199], v[44:47]
	v_mfma_f32_16x16x32_bf16 v[48:51], v[128:131], v[204:207], v[48:51]
	v_mfma_f32_16x16x32_bf16 v[52:55], v[168:171], v[204:207], v[52:55]
	v_mfma_f32_16x16x32_bf16 v[56:59], v[128:131], v[212:215], v[56:59]
	v_mfma_f32_16x16x32_bf16 v[60:63], v[168:171], v[212:215], v[60:63]
	s_setprio 0
	s_barrier
	s_mov_b32 m0, s63
	v_lshl_add_u64 v[236:237], s[26:27], 0, v[2:3]
	s_add_u32 s8, s26, 0x40000
	ds_read_b128 v[92:95], v151 offset:16384
	ds_read_b128 v[96:99], v151 offset:17408
	ds_read_b128 v[172:175], v151 offset:18432
	ds_read_b128 v[176:179], v151 offset:19456
	ds_read_b128 v[180:183], v151 offset:20480
	ds_read_b128 v[196:199], v151 offset:21504
	ds_read_b128 v[200:203], v151 offset:22528
	ds_read_b128 v[204:207], v151 offset:23552
	global_load_lds_dwordx4 v[236:237], off
	v_lshl_add_u64 v[242:243], s[26:27], 0, v[134:135]
	s_mov_b32 m0, s9
	s_addc_u32 s9, s27, 0
	global_load_lds_dwordx4 v[242:243], off
	v_lshl_add_u64 v[184:185], s[8:9], 0, v[2:3]
	s_mov_b32 m0, s24
	v_lshl_add_u64 v[252:253], s[0:1], 0, v[0:1]
	global_load_lds_dwordx4 v[184:185], off
	v_lshl_add_u64 v[184:185], s[8:9], 0, v[134:135]
	s_mov_b32 m0, s62
	v_lshl_add_u64 v[188:189], s[0:1], 0, v[132:133]
	global_load_lds_dwordx4 v[184:185], off
	s_mov_b32 m0, s58
	s_nop 0
	global_load_lds_dwordx4 v[252:253], off
	s_mov_b32 m0, s59
	s_nop 0
	global_load_lds_dwordx4 v[188:189], off
	s_waitcnt vmcnt(8)
	s_waitcnt lgkmcnt(0)
	s_barrier
	s_setprio 1
	v_mfma_f32_16x16x32_bf16 v[4:7], v[108:111], v[200:203], v[4:7]
	v_mfma_f32_16x16x32_bf16 v[8:11], v[116:119], v[200:203], v[8:11]
	v_mfma_f32_16x16x32_bf16 v[136:139], v[108:111], v[92:95], v[136:139]
	v_mfma_f32_16x16x32_bf16 v[140:143], v[116:119], v[92:95], v[140:143]
	v_mfma_f32_16x16x32_bf16 v[144:147], v[108:111], v[172:175], v[144:147]
	v_mfma_f32_16x16x32_bf16 v[152:155], v[116:119], v[172:175], v[152:155]
	v_mfma_f32_16x16x32_bf16 v[156:159], v[108:111], v[180:183], v[156:159]
	v_mfma_f32_16x16x32_bf16 v[160:163], v[116:119], v[180:183], v[160:163]
	v_mfma_f32_16x16x32_bf16 v[4:7], v[112:115], v[204:207], v[4:7]
	v_mfma_f32_16x16x32_bf16 v[8:11], v[120:123], v[204:207], v[8:11]
	v_mfma_f32_16x16x32_bf16 v[136:139], v[112:115], v[96:99], v[136:139]
	v_mfma_f32_16x16x32_bf16 v[140:143], v[120:123], v[96:99], v[140:143]
	v_mfma_f32_16x16x32_bf16 v[144:147], v[112:115], v[176:179], v[144:147]
	v_mfma_f32_16x16x32_bf16 v[152:155], v[120:123], v[176:179], v[152:155]
	v_mfma_f32_16x16x32_bf16 v[156:159], v[112:115], v[196:199], v[156:159]
	v_mfma_f32_16x16x32_bf16 v[160:163], v[120:123], v[196:199], v[160:163]
	v_mfma_f32_16x16x32_bf16 v[12:15], v[124:127], v[92:95], v[12:15]
	v_mfma_f32_16x16x32_bf16 v[208:211], v[128:131], v[96:99], v[12:15]
	v_mfma_f32_16x16x32_bf16 v[12:15], v[164:167], v[92:95], v[16:19]
	v_mfma_f32_16x16x32_bf16 v[212:215], v[168:171], v[96:99], v[12:15]
	v_mfma_f32_16x16x32_bf16 v[12:15], v[124:127], v[172:175], v[28:31]
	v_mfma_f32_16x16x32_bf16 v[224:227], v[128:131], v[176:179], v[12:15]
	v_mfma_f32_16x16x32_bf16 v[12:15], v[164:167], v[172:175], v[32:35]
	v_mfma_f32_16x16x32_bf16 v[172:175], v[168:171], v[176:179], v[12:15]
	v_mfma_f32_16x16x32_bf16 v[12:15], v[124:127], v[180:183], v[64:67]
	v_mfma_f32_16x16x32_bf16 v[176:179], v[128:131], v[196:199], v[12:15]
	v_mfma_f32_16x16x32_bf16 v[12:15], v[164:167], v[180:183], v[104:107]
	v_mfma_f32_16x16x32_bf16 v[180:183], v[168:171], v[196:199], v[12:15]
	v_mfma_f32_16x16x32_bf16 v[12:15], v[124:127], v[200:203], v[20:23]
	v_mfma_f32_16x16x32_bf16 v[196:199], v[128:131], v[204:207], v[12:15]
	v_mfma_f32_16x16x32_bf16 v[12:15], v[164:167], v[200:203], v[24:27]
	v_mfma_f32_16x16x32_bf16 v[164:167], v[168:171], v[204:207], v[12:15]
	s_setprio 0
	s_barrier
	s_nop 4
	ds_read_b128 v[12:15], v228
	ds_read_b128 v[16:19], v228 offset:1024
	ds_read_b128 v[20:23], v228 offset:2048
	ds_read_b128 v[24:27], v228 offset:3072
	ds_read_b128 v[168:171], v229
	ds_read_b128 v[200:203], v229 offset:1024
	ds_read_b128 v[204:207], v229 offset:2048
	ds_read_b128 v[244:247], v229 offset:3072
	s_add_u32 s8, s0, 0x40000
	s_addc_u32 s9, s1, 0
	s_mov_b32 m0, s61
	v_lshl_add_u64 v[92:93], s[8:9], 0, v[0:1]
	ds_read_b128 v[28:31], v151 offset:32768
	ds_read_b128 v[32:35], v151 offset:33792
	ds_read_b128 v[64:67], v151 offset:34816
	ds_read_b128 v[248:251], v151 offset:35840
	ds_read_b128 v[232:235], v151 offset:36864
	ds_read_b128 v[192:195], v151 offset:37888
	ds_read_b128 v[184:187], v151 offset:38912
	ds_read_b128 v[228:231], v151 offset:39936
	global_load_lds_dwordx4 v[92:93], off
	v_lshl_add_u64 v[92:93], s[8:9], 0, v[132:133]
	s_mov_b32 m0, s72
	s_nop 0
	global_load_lds_dwordx4 v[92:93], off
	s_waitcnt vmcnt(8)
	s_waitcnt lgkmcnt(0)
	s_barrier
	s_setprio 1
	v_mfma_f32_16x16x32_bf16 v[68:71], v[12:15], v[28:31], v[68:71]
	v_mfma_f32_16x16x32_bf16 v[128:131], v[16:19], v[32:35], v[68:71]
	v_mfma_f32_16x16x32_bf16 v[68:71], v[20:23], v[28:31], v[72:75]
	v_mfma_f32_16x16x32_bf16 v[124:127], v[24:27], v[32:35], v[68:71]
	v_mfma_f32_16x16x32_bf16 v[68:71], v[12:15], v[64:67], v[76:79]
	v_mfma_f32_16x16x32_bf16 v[112:115], v[16:19], v[248:251], v[68:71]
	v_mfma_f32_16x16x32_bf16 v[68:71], v[20:23], v[64:67], v[80:83]
	v_mfma_f32_16x16x32_bf16 v[108:111], v[24:27], v[248:251], v[68:71]
	v_mfma_f32_16x16x32_bf16 v[68:71], v[12:15], v[232:235], v[84:87]
	v_mfma_f32_16x16x32_bf16 v[96:99], v[16:19], v[192:195], v[68:71]
	v_mfma_f32_16x16x32_bf16 v[68:71], v[20:23], v[232:235], v[88:91]
	v_mfma_f32_16x16x32_bf16 v[92:95], v[24:27], v[192:195], v[68:71]
	v_mfma_f32_16x16x32_bf16 v[68:71], v[12:15], v[184:187], v[216:219]
	v_mfma_f32_16x16x32_bf16 v[80:83], v[16:19], v[228:231], v[68:71]
	v_mfma_f32_16x16x32_bf16 v[68:71], v[20:23], v[184:187], v[220:223]
	v_mfma_f32_16x16x32_bf16 v[76:79], v[24:27], v[228:231], v[68:71]
	v_mfma_f32_16x16x32_bf16 v[68:71], v[168:171], v[28:31], v[100:103]
	v_mfma_f32_16x16x32_bf16 v[28:31], v[204:207], v[28:31], v[36:39]
	v_mfma_f32_16x16x32_bf16 v[116:119], v[244:247], v[32:35], v[28:31]
	v_mfma_f32_16x16x32_bf16 v[28:31], v[168:171], v[64:67], v[40:43]
	v_mfma_f32_16x16x32_bf16 v[104:107], v[200:203], v[248:251], v[28:31]
	v_mfma_f32_16x16x32_bf16 v[28:31], v[204:207], v[64:67], v[44:47]
	v_mfma_f32_16x16x32_bf16 v[100:103], v[244:247], v[248:251], v[28:31]
	v_mfma_f32_16x16x32_bf16 v[28:31], v[168:171], v[232:235], v[48:51]
	v_mfma_f32_16x16x32_bf16 v[88:91], v[200:203], v[192:195], v[28:31]
	v_mfma_f32_16x16x32_bf16 v[28:31], v[204:207], v[232:235], v[52:55]
	v_mfma_f32_16x16x32_bf16 v[84:87], v[244:247], v[192:195], v[28:31]
	v_mfma_f32_16x16x32_bf16 v[28:31], v[168:171], v[184:187], v[56:59]
	v_mfma_f32_16x16x32_bf16 v[72:75], v[200:203], v[228:231], v[28:31]
	v_mfma_f32_16x16x32_bf16 v[28:31], v[204:207], v[184:187], v[60:63]
	v_mfma_f32_16x16x32_bf16 v[120:123], v[200:203], v[32:35], v[68:71]
	v_mfma_f32_16x16x32_bf16 v[68:71], v[244:247], v[228:231], v[28:31]
	s_setprio 0
	s_barrier
	s_mov_b32 m0, s87
	s_nop 2
	v_lshl_add_u64 v[28:29], v[236:237], 0, s[46:47]
	s_add_u32 s8, s26, 0x40080
	ds_read_b128 v[36:39], v151 offset:49152
	ds_read_b128 v[40:43], v151 offset:50176
	ds_read_b128 v[184:187], v151 offset:51200
	ds_read_b128 v[192:195], v151 offset:52224
	ds_read_b128 v[216:219], v151 offset:53248
	ds_read_b128 v[220:223], v151 offset:54272
	ds_read_b128 v[228:231], v151 offset:55296
	ds_read_b128 v[232:235], v151 offset:56320
	global_load_lds_dwordx4 v[28:29], off
	v_lshl_add_u64 v[28:29], v[242:243], 0, s[46:47]
	s_mov_b32 m0, s65
	s_addc_u32 s9, s27, 0
	global_load_lds_dwordx4 v[28:29], off
	v_lshl_add_u64 v[28:29], s[8:9], 0, v[2:3]
	s_mov_b32 m0, s44
	s_nop 0
	global_load_lds_dwordx4 v[28:29], off
	v_lshl_add_u64 v[28:29], s[8:9], 0, v[134:135]
	s_mov_b32 m0, s45
	s_nop 0
	global_load_lds_dwordx4 v[28:29], off
	v_lshl_add_u64 v[28:29], v[252:253], 0, s[46:47]
	s_mov_b32 m0, s74
	s_nop 0
	global_load_lds_dwordx4 v[28:29], off
	v_lshl_add_u64 v[28:29], v[188:189], 0, s[46:47]
	s_mov_b32 m0, s75
	s_nop 0
	global_load_lds_dwordx4 v[28:29], off
	s_waitcnt vmcnt(8)
	s_waitcnt lgkmcnt(0)
	s_barrier
	s_setprio 1
	v_mfma_f32_16x16x32_bf16 v[28:31], v[12:15], v[36:39], v[136:139]
	v_mfma_f32_16x16x32_bf16 v[64:67], v[16:19], v[40:43], v[28:31]
	v_mfma_f32_16x16x32_bf16 v[28:31], v[20:23], v[36:39], v[140:143]
	v_mfma_f32_16x16x32_bf16 v[60:63], v[24:27], v[40:43], v[28:31]
	v_mfma_f32_16x16x32_bf16 v[28:31], v[12:15], v[184:187], v[144:147]
	v_mfma_f32_16x16x32_bf16 v[48:51], v[16:19], v[192:195], v[28:31]
	v_mfma_f32_16x16x32_bf16 v[28:31], v[20:23], v[184:187], v[152:155]
	v_mfma_f32_16x16x32_bf16 v[44:47], v[24:27], v[192:195], v[28:31]
	v_mfma_f32_16x16x32_bf16 v[28:31], v[12:15], v[216:219], v[156:159]
	v_mfma_f32_16x16x32_bf16 v[4:7], v[12:15], v[228:231], v[4:7]
	v_mfma_f32_16x16x32_bf16 v[32:35], v[16:19], v[220:223], v[28:31]
	v_mfma_f32_16x16x32_bf16 v[28:31], v[20:23], v[216:219], v[160:163]
	v_mfma_f32_16x16x32_bf16 v[16:19], v[16:19], v[232:235], v[4:7]
	v_mfma_f32_16x16x32_bf16 v[4:7], v[20:23], v[228:231], v[8:11]
	v_mfma_f32_16x16x32_bf16 v[28:31], v[24:27], v[220:223], v[28:31]
	v_mfma_f32_16x16x32_bf16 v[12:15], v[24:27], v[232:235], v[4:7]
	v_mfma_f32_16x16x32_bf16 v[4:7], v[168:171], v[36:39], v[208:211]
	v_mfma_f32_16x16x32_bf16 v[56:59], v[200:203], v[40:43], v[4:7]
	v_mfma_f32_16x16x32_bf16 v[4:7], v[204:207], v[36:39], v[212:215]
	v_mfma_f32_16x16x32_bf16 v[52:55], v[244:247], v[40:43], v[4:7]
	v_mfma_f32_16x16x32_bf16 v[4:7], v[168:171], v[184:187], v[224:227]
	v_mfma_f32_16x16x32_bf16 v[40:43], v[200:203], v[192:195], v[4:7]
	v_mfma_f32_16x16x32_bf16 v[4:7], v[204:207], v[184:187], v[172:175]
	v_mfma_f32_16x16x32_bf16 v[36:39], v[244:247], v[192:195], v[4:7]
	v_mfma_f32_16x16x32_bf16 v[4:7], v[168:171], v[216:219], v[176:179]
	v_mfma_f32_16x16x32_bf16 v[24:27], v[200:203], v[220:223], v[4:7]
	v_mfma_f32_16x16x32_bf16 v[4:7], v[204:207], v[216:219], v[180:183]
	v_mfma_f32_16x16x32_bf16 v[20:23], v[244:247], v[220:223], v[4:7]
	v_mfma_f32_16x16x32_bf16 v[4:7], v[168:171], v[228:231], v[196:199]
	v_mfma_f32_16x16x32_bf16 v[8:11], v[200:203], v[232:235], v[4:7]
	v_mfma_f32_16x16x32_bf16 v[4:7], v[204:207], v[228:231], v[164:167]
	v_mfma_f32_16x16x32_bf16 v[4:7], v[244:247], v[232:235], v[4:7]
	s_setprio 0
	s_barrier
	s_andn2_b64 vcc, exec, s[84:85]
	s_cbranch_vccnz .LBB0_551
	s_barrier

.LBB0_770:
	s_add_i32 s65, s42, 2
	s_add_u32 vcc_lo, s6, 0x80
	s_addc_u32 s43, s7, 0
	s_add_i32 s9, 0, 0x10000
	s_cmp_eq_u32 s72, s42
	s_cselect_b32 s43, s17, s43
	s_cselect_b32 s42, s16, vcc_lo
	s_cselect_b32 vcc_hi, s19, s53
	s_cselect_b32 vcc_lo, s18, s52
	s_add_i32 s67, 0, 0x14000
	v_add_u32_e32 v144, s9, v180
	v_add_u32_e32 v160, s67, v180
	ds_read_b128 v[132:135], v144
	ds_read_b128 v[136:139], v144 offset:1024
	ds_read_b128 v[140:143], v144 offset:2048
	ds_read_b128 v[144:147], v144 offset:3072
	ds_read_b128 v[148:151], v160
	ds_read_b128 v[152:155], v160 offset:1024
	ds_read_b128 v[156:159], v160 offset:2048
	ds_read_b128 v[160:163], v160 offset:3072
	v_lshl_add_u64 v[176:177], s[6:7], 0, v[168:169]
	s_add_i32 m0, s63, 0xc000
	ds_read_b128 v[172:175], v181
	ds_read_b128 v[196:199], v181 offset:1024
	ds_read_b128 v[200:203], v181 offset:2048
	ds_read_b128 v[204:207], v181 offset:3072
	ds_read_b128 v[208:211], v181 offset:4096
	ds_read_b128 v[212:215], v181 offset:5120
	ds_read_b128 v[216:219], v181 offset:6144
	ds_read_b128 v[220:223], v181 offset:7168
	global_load_lds_dwordx4 v[176:177], off
	v_lshl_add_u64 v[176:177], s[6:7], 0, v[170:171]
	s_add_i32 m0, s63, 0xe000
	s_nop 0
	global_load_lds_dwordx4 v[176:177], off
	s_waitcnt vmcnt(8)
	s_waitcnt lgkmcnt(0)
	s_barrier
	s_setprio 1
	v_mfma_f32_16x16x32_bf16 v[128:131], v[132:135], v[172:175], v[128:131]
	v_mfma_f32_16x16x32_bf16 v[124:127], v[140:143], v[172:175], v[124:127]
	v_mfma_f32_16x16x32_bf16 v[112:115], v[132:135], v[200:203], v[112:115]
	v_mfma_f32_16x16x32_bf16 v[108:111], v[140:143], v[200:203], v[108:111]
	v_mfma_f32_16x16x32_bf16 v[96:99], v[132:135], v[208:211], v[96:99]
	v_mfma_f32_16x16x32_bf16 v[92:95], v[140:143], v[208:211], v[92:95]
	v_mfma_f32_16x16x32_bf16 v[80:83], v[132:135], v[216:219], v[80:83]
	v_mfma_f32_16x16x32_bf16 v[76:79], v[140:143], v[216:219], v[76:79]
	v_mfma_f32_16x16x32_bf16 v[128:131], v[136:139], v[196:199], v[128:131]
	v_mfma_f32_16x16x32_bf16 v[124:127], v[144:147], v[196:199], v[124:127]
	v_mfma_f32_16x16x32_bf16 v[112:115], v[136:139], v[204:207], v[112:115]
	v_mfma_f32_16x16x32_bf16 v[108:111], v[144:147], v[204:207], v[108:111]
	v_mfma_f32_16x16x32_bf16 v[96:99], v[136:139], v[212:215], v[96:99]
	v_mfma_f32_16x16x32_bf16 v[92:95], v[144:147], v[212:215], v[92:95]
	v_mfma_f32_16x16x32_bf16 v[80:83], v[136:139], v[220:223], v[80:83]
	v_mfma_f32_16x16x32_bf16 v[76:79], v[144:147], v[220:223], v[76:79]
	v_mfma_f32_16x16x32_bf16 v[120:123], v[148:151], v[172:175], v[120:123]
	v_mfma_f32_16x16x32_bf16 v[116:119], v[156:159], v[172:175], v[116:119]
	v_mfma_f32_16x16x32_bf16 v[104:107], v[148:151], v[200:203], v[104:107]
	v_mfma_f32_16x16x32_bf16 v[100:103], v[156:159], v[200:203], v[100:103]
	v_mfma_f32_16x16x32_bf16 v[88:91], v[148:151], v[208:211], v[88:91]
	v_mfma_f32_16x16x32_bf16 v[84:87], v[156:159], v[208:211], v[84:87]
	v_mfma_f32_16x16x32_bf16 v[72:75], v[148:151], v[216:219], v[72:75]
	v_mfma_f32_16x16x32_bf16 v[68:71], v[156:159], v[216:219], v[68:71]
	v_mfma_f32_16x16x32_bf16 v[120:123], v[152:155], v[196:199], v[120:123]
	v_mfma_f32_16x16x32_bf16 v[116:119], v[160:163], v[196:199], v[116:119]
	v_mfma_f32_16x16x32_bf16 v[104:107], v[152:155], v[204:207], v[104:107]
	v_mfma_f32_16x16x32_bf16 v[100:103], v[160:163], v[204:207], v[100:103]
	v_mfma_f32_16x16x32_bf16 v[88:91], v[152:155], v[212:215], v[88:91]
	v_mfma_f32_16x16x32_bf16 v[84:87], v[160:163], v[212:215], v[84:87]
	v_mfma_f32_16x16x32_bf16 v[72:75], v[152:155], v[220:223], v[72:75]
	v_mfma_f32_16x16x32_bf16 v[68:71], v[160:163], v[220:223], v[68:71]
	s_setprio 0
	s_barrier
	s_add_i32 s9, s9, s62
	v_lshl_add_u64 v[176:177], vcc, 0, v[2:3]
	s_mov_b32 m0, s9
	ds_read_b128 v[172:175], v181 offset:16384
	ds_read_b128 v[196:199], v181 offset:17408
	ds_read_b128 v[200:203], v181 offset:18432
	ds_read_b128 v[204:207], v181 offset:19456
	ds_read_b128 v[208:211], v181 offset:20480
	ds_read_b128 v[212:215], v181 offset:21504
	ds_read_b128 v[216:219], v181 offset:22528
	ds_read_b128 v[220:223], v181 offset:23552
	global_load_lds_dwordx4 v[176:177], off
	s_add_i32 m0, s9, 0x2000
	v_lshl_add_u64 v[182:183], vcc, 0, v[166:167]
	s_add_u32 vcc_lo, vcc_lo, s55
	s_addc_u32 vcc_hi, vcc_hi, 0
	s_add_i32 s9, s67, s62
	global_load_lds_dwordx4 v[182:183], off
	v_lshl_add_u64 v[184:185], vcc, 0, v[2:3]
	s_mov_b32 m0, s9
	v_lshl_add_u64 v[186:187], vcc, 0, v[166:167]
	global_load_lds_dwordx4 v[184:185], off
	s_add_i32 m0, s9, 0x2000
	v_lshl_add_u64 v[192:193], s[42:43], 0, v[0:1]
	global_load_lds_dwordx4 v[186:187], off
	s_mov_b32 m0, s63
	v_lshl_add_u64 v[194:195], s[42:43], 0, v[164:165]
	global_load_lds_dwordx4 v[192:193], off
	s_mov_b32 m0, s86
	s_nop 0
	global_load_lds_dwordx4 v[194:195], off
	s_waitcnt vmcnt(8)
	s_waitcnt lgkmcnt(0)
	s_barrier
	s_setprio 1
	v_mfma_f32_16x16x32_bf16 v[64:67], v[132:135], v[172:175], v[64:67]
	v_mfma_f32_16x16x32_bf16 v[60:63], v[140:143], v[172:175], v[60:63]
	v_mfma_f32_16x16x32_bf16 v[48:51], v[132:135], v[200:203], v[48:51]
	v_mfma_f32_16x16x32_bf16 v[44:47], v[140:143], v[200:203], v[44:47]
	v_mfma_f32_16x16x32_bf16 v[32:35], v[132:135], v[208:211], v[32:35]
	v_mfma_f32_16x16x32_bf16 v[28:31], v[140:143], v[208:211], v[28:31]
	v_mfma_f32_16x16x32_bf16 v[16:19], v[132:135], v[216:219], v[16:19]
	v_mfma_f32_16x16x32_bf16 v[12:15], v[140:143], v[216:219], v[12:15]
	v_mfma_f32_16x16x32_bf16 v[64:67], v[136:139], v[196:199], v[64:67]
	v_mfma_f32_16x16x32_bf16 v[60:63], v[144:147], v[196:199], v[60:63]
	v_mfma_f32_16x16x32_bf16 v[48:51], v[136:139], v[204:207], v[48:51]
	v_mfma_f32_16x16x32_bf16 v[44:47], v[144:147], v[204:207], v[44:47]
	v_mfma_f32_16x16x32_bf16 v[32:35], v[136:139], v[212:215], v[32:35]
	v_mfma_f32_16x16x32_bf16 v[28:31], v[144:147], v[212:215], v[28:31]
	v_mfma_f32_16x16x32_bf16 v[16:19], v[136:139], v[220:223], v[16:19]
	v_mfma_f32_16x16x32_bf16 v[12:15], v[144:147], v[220:223], v[12:15]
	v_mfma_f32_16x16x32_bf16 v[56:59], v[148:151], v[172:175], v[56:59]
	v_mfma_f32_16x16x32_bf16 v[52:55], v[156:159], v[172:175], v[52:55]
	v_mfma_f32_16x16x32_bf16 v[40:43], v[148:151], v[200:203], v[40:43]
	v_mfma_f32_16x16x32_bf16 v[36:39], v[156:159], v[200:203], v[36:39]
	v_mfma_f32_16x16x32_bf16 v[24:27], v[148:151], v[208:211], v[24:27]
	v_mfma_f32_16x16x32_bf16 v[20:23], v[156:159], v[208:211], v[20:23]
	v_mfma_f32_16x16x32_bf16 v[8:11], v[148:151], v[216:219], v[8:11]
	v_mfma_f32_16x16x32_bf16 v[4:7], v[156:159], v[216:219], v[4:7]
	v_mfma_f32_16x16x32_bf16 v[56:59], v[152:155], v[196:199], v[56:59]
	v_mfma_f32_16x16x32_bf16 v[52:55], v[160:163], v[196:199], v[52:55]
	v_mfma_f32_16x16x32_bf16 v[40:43], v[152:155], v[204:207], v[40:43]
	v_mfma_f32_16x16x32_bf16 v[36:39], v[160:163], v[204:207], v[36:39]
	v_mfma_f32_16x16x32_bf16 v[24:27], v[152:155], v[212:215], v[24:27]
	v_mfma_f32_16x16x32_bf16 v[20:23], v[160:163], v[212:215], v[20:23]
	v_mfma_f32_16x16x32_bf16 v[8:11], v[152:155], v[220:223], v[8:11]
	v_mfma_f32_16x16x32_bf16 v[4:7], v[160:163], v[220:223], v[4:7]
	s_setprio 0
	s_barrier
	s_add_i32 s9, 0, 0x18000
	s_add_i32 s67, 0, 0x1c000
	v_add_u32_e32 v144, s9, v180
	v_add_u32_e32 v160, s67, v180
	ds_read_b128 v[132:135], v144
	ds_read_b128 v[136:139], v144 offset:1024
	ds_read_b128 v[140:143], v144 offset:2048
	ds_read_b128 v[144:147], v144 offset:3072
	ds_read_b128 v[148:151], v160
	ds_read_b128 v[152:155], v160 offset:1024
	ds_read_b128 v[156:159], v160 offset:2048
	ds_read_b128 v[160:163], v160 offset:3072
	s_add_u32 s42, s42, s24
	s_addc_u32 s43, s43, 0
	s_mov_b32 m0, s87
	v_lshl_add_u64 v[224:225], s[42:43], 0, v[0:1]
	ds_read_b128 v[172:175], v181 offset:32768
	ds_read_b128 v[196:199], v181 offset:33792
	ds_read_b128 v[200:203], v181 offset:34816
	ds_read_b128 v[204:207], v181 offset:35840
	ds_read_b128 v[208:211], v181 offset:36864
	ds_read_b128 v[212:215], v181 offset:37888
	ds_read_b128 v[216:219], v181 offset:38912
	ds_read_b128 v[220:223], v181 offset:39936
	global_load_lds_dwordx4 v[224:225], off
	v_lshl_add_u64 v[224:225], s[42:43], 0, v[164:165]
	s_mov_b32 m0, s58
	s_nop 0
	global_load_lds_dwordx4 v[224:225], off
	s_waitcnt vmcnt(8)
	s_waitcnt lgkmcnt(0)
	s_barrier
	s_setprio 1
	v_mfma_f32_16x16x32_bf16 v[128:131], v[132:135], v[172:175], v[128:131]
	v_mfma_f32_16x16x32_bf16 v[124:127], v[140:143], v[172:175], v[124:127]
	v_mfma_f32_16x16x32_bf16 v[112:115], v[132:135], v[200:203], v[112:115]
	v_mfma_f32_16x16x32_bf16 v[108:111], v[140:143], v[200:203], v[108:111]
	v_mfma_f32_16x16x32_bf16 v[96:99], v[132:135], v[208:211], v[96:99]
	v_mfma_f32_16x16x32_bf16 v[92:95], v[140:143], v[208:211], v[92:95]
	v_mfma_f32_16x16x32_bf16 v[80:83], v[132:135], v[216:219], v[80:83]
	v_mfma_f32_16x16x32_bf16 v[76:79], v[140:143], v[216:219], v[76:79]
	v_mfma_f32_16x16x32_bf16 v[128:131], v[136:139], v[196:199], v[128:131]
	v_mfma_f32_16x16x32_bf16 v[124:127], v[144:147], v[196:199], v[124:127]
	v_mfma_f32_16x16x32_bf16 v[112:115], v[136:139], v[204:207], v[112:115]
	v_mfma_f32_16x16x32_bf16 v[108:111], v[144:147], v[204:207], v[108:111]
	v_mfma_f32_16x16x32_bf16 v[96:99], v[136:139], v[212:215], v[96:99]
	v_mfma_f32_16x16x32_bf16 v[92:95], v[144:147], v[212:215], v[92:95]
	v_mfma_f32_16x16x32_bf16 v[80:83], v[136:139], v[220:223], v[80:83]
	v_mfma_f32_16x16x32_bf16 v[76:79], v[144:147], v[220:223], v[76:79]
	v_mfma_f32_16x16x32_bf16 v[120:123], v[148:151], v[172:175], v[120:123]
	v_mfma_f32_16x16x32_bf16 v[116:119], v[156:159], v[172:175], v[116:119]
	v_mfma_f32_16x16x32_bf16 v[104:107], v[148:151], v[200:203], v[104:107]
	v_mfma_f32_16x16x32_bf16 v[100:103], v[156:159], v[200:203], v[100:103]
	v_mfma_f32_16x16x32_bf16 v[88:91], v[148:151], v[208:211], v[88:91]
	v_mfma_f32_16x16x32_bf16 v[84:87], v[156:159], v[208:211], v[84:87]
	v_mfma_f32_16x16x32_bf16 v[72:75], v[148:151], v[216:219], v[72:75]
	v_mfma_f32_16x16x32_bf16 v[68:71], v[156:159], v[216:219], v[68:71]
	v_mfma_f32_16x16x32_bf16 v[120:123], v[152:155], v[196:199], v[120:123]
	v_mfma_f32_16x16x32_bf16 v[116:119], v[160:163], v[196:199], v[116:119]
	v_mfma_f32_16x16x32_bf16 v[104:107], v[152:155], v[204:207], v[104:107]
	v_mfma_f32_16x16x32_bf16 v[100:103], v[160:163], v[204:207], v[100:103]
	v_mfma_f32_16x16x32_bf16 v[88:91], v[152:155], v[212:215], v[88:91]
	v_mfma_f32_16x16x32_bf16 v[84:87], v[160:163], v[212:215], v[84:87]
	v_mfma_f32_16x16x32_bf16 v[72:75], v[152:155], v[220:223], v[72:75]
	v_mfma_f32_16x16x32_bf16 v[68:71], v[160:163], v[220:223], v[68:71]
	s_setprio 0
	s_barrier
	s_add_i32 s9, s9, s62
	v_lshl_add_u64 v[176:177], v[176:177], 0, s[46:47]
	s_mov_b32 m0, s9
	ds_read_b128 v[172:175], v181 offset:49152
	ds_read_b128 v[196:199], v181 offset:50176
	ds_read_b128 v[200:203], v181 offset:51200
	ds_read_b128 v[204:207], v181 offset:52224
	ds_read_b128 v[208:211], v181 offset:53248
	ds_read_b128 v[212:215], v181 offset:54272
	ds_read_b128 v[216:219], v181 offset:55296
	ds_read_b128 v[220:223], v181 offset:56320
	global_load_lds_dwordx4 v[176:177], off
	v_lshl_add_u64 v[176:177], v[182:183], 0, s[46:47]
	s_add_i32 m0, s9, 0x2000
	s_add_i32 s9, s67, s62
	global_load_lds_dwordx4 v[176:177], off
	v_lshl_add_u64 v[176:177], v[184:185], 0, s[46:47]
	s_mov_b32 m0, s9
	s_nop 0
	global_load_lds_dwordx4 v[176:177], off
	v_lshl_add_u64 v[176:177], v[186:187], 0, s[46:47]
	s_add_i32 m0, s9, 0x2000
	s_nop 0
	global_load_lds_dwordx4 v[176:177], off
	v_lshl_add_u64 v[176:177], v[192:193], 0, s[46:47]
	s_mov_b32 m0, s50
	s_nop 0
	global_load_lds_dwordx4 v[176:177], off
	v_lshl_add_u64 v[176:177], v[194:195], 0, s[46:47]
	s_mov_b32 m0, s51
	s_nop 0
	global_load_lds_dwordx4 v[176:177], off
	s_waitcnt vmcnt(8)
	s_waitcnt lgkmcnt(0)
	s_barrier
	s_setprio 1
	v_mfma_f32_16x16x32_bf16 v[64:67], v[132:135], v[172:175], v[64:67]
	v_mfma_f32_16x16x32_bf16 v[60:63], v[140:143], v[172:175], v[60:63]
	v_mfma_f32_16x16x32_bf16 v[48:51], v[132:135], v[200:203], v[48:51]
	v_mfma_f32_16x16x32_bf16 v[44:47], v[140:143], v[200:203], v[44:47]
	v_mfma_f32_16x16x32_bf16 v[32:35], v[132:135], v[208:211], v[32:35]
	v_mfma_f32_16x16x32_bf16 v[28:31], v[140:143], v[208:211], v[28:31]
	v_mfma_f32_16x16x32_bf16 v[16:19], v[132:135], v[216:219], v[16:19]
	v_mfma_f32_16x16x32_bf16 v[12:15], v[140:143], v[216:219], v[12:15]
	v_mfma_f32_16x16x32_bf16 v[64:67], v[136:139], v[196:199], v[64:67]
	v_mfma_f32_16x16x32_bf16 v[60:63], v[144:147], v[196:199], v[60:63]
	v_mfma_f32_16x16x32_bf16 v[48:51], v[136:139], v[204:207], v[48:51]
	v_mfma_f32_16x16x32_bf16 v[44:47], v[144:147], v[204:207], v[44:47]
	v_mfma_f32_16x16x32_bf16 v[32:35], v[136:139], v[212:215], v[32:35]
	v_mfma_f32_16x16x32_bf16 v[28:31], v[144:147], v[212:215], v[28:31]
	v_mfma_f32_16x16x32_bf16 v[16:19], v[136:139], v[220:223], v[16:19]
	v_mfma_f32_16x16x32_bf16 v[12:15], v[144:147], v[220:223], v[12:15]
	v_mfma_f32_16x16x32_bf16 v[56:59], v[148:151], v[172:175], v[56:59]
	v_mfma_f32_16x16x32_bf16 v[52:55], v[156:159], v[172:175], v[52:55]
	v_mfma_f32_16x16x32_bf16 v[40:43], v[148:151], v[200:203], v[40:43]
	v_mfma_f32_16x16x32_bf16 v[36:39], v[156:159], v[200:203], v[36:39]
	v_mfma_f32_16x16x32_bf16 v[24:27], v[148:151], v[208:211], v[24:27]
	v_mfma_f32_16x16x32_bf16 v[20:23], v[156:159], v[208:211], v[20:23]
	v_mfma_f32_16x16x32_bf16 v[8:11], v[148:151], v[216:219], v[8:11]
	v_mfma_f32_16x16x32_bf16 v[4:7], v[156:159], v[216:219], v[4:7]
	v_mfma_f32_16x16x32_bf16 v[56:59], v[152:155], v[196:199], v[56:59]
	v_mfma_f32_16x16x32_bf16 v[52:55], v[160:163], v[196:199], v[52:55]
	v_mfma_f32_16x16x32_bf16 v[40:43], v[152:155], v[204:207], v[40:43]
	v_mfma_f32_16x16x32_bf16 v[36:39], v[160:163], v[204:207], v[36:39]
	v_mfma_f32_16x16x32_bf16 v[24:27], v[152:155], v[212:215], v[24:27]
	v_mfma_f32_16x16x32_bf16 v[20:23], v[160:163], v[212:215], v[20:23]
	v_mfma_f32_16x16x32_bf16 v[8:11], v[152:155], v[220:223], v[8:11]
	v_mfma_f32_16x16x32_bf16 v[4:7], v[160:163], v[220:223], v[4:7]
	s_setprio 0
	s_barrier
	s_add_u32 s6, s6, 0x100
	s_addc_u32 s7, s7, 0
	s_add_u32 s52, s52, 0x100
	s_addc_u32 s53, s53, 0
	s_cmp_ge_u32 s65, s39
	s_mov_b32 s42, s65
	s_cbranch_scc0 .LBB0_770
	s_and_b64 vcc, exec, s[12:13]
	s_cbranch_vccz .LBB0_773
	s_barrier

.LBB0_939:
	s_add_i32 s50, s40, 2
	s_add_u32 s51, s38, 0x80
	s_addc_u32 s41, s39, 0
	s_add_i32 s65, 0, 0x10000
	s_cmp_eq_u32 s73, s40
	s_cselect_b32 s41, s7, s41
	s_cselect_b32 s40, s6, s51
	s_cselect_b32 s63, s29, s35
	s_cselect_b32 s62, s28, s31
	s_add_i32 s51, 0, 0x14000
	v_add_u32_e32 v144, s65, v200
	v_add_u32_e32 v168, s51, v200
	ds_read_b128 v[132:135], v144
	ds_read_b128 v[136:139], v144 offset:1024
	ds_read_b128 v[140:143], v144 offset:2048
	ds_read_b128 v[144:147], v144 offset:3072
	ds_read_b128 v[148:151], v168
	ds_read_b128 v[152:155], v168 offset:1024
	ds_read_b128 v[156:159], v168 offset:2048
	ds_read_b128 v[168:171], v168 offset:3072
	v_lshl_add_u64 v[184:185], s[38:39], 0, v[164:165]
	s_add_i32 m0, s48, 0xc000
	ds_read_b128 v[172:175], v201
	ds_read_b128 v[176:179], v201 offset:1024
	ds_read_b128 v[180:183], v201 offset:2048
	ds_read_b128 v[202:205], v201 offset:3072
	ds_read_b128 v[206:209], v201 offset:4096
	ds_read_b128 v[210:213], v201 offset:5120
	ds_read_b128 v[214:217], v201 offset:6144
	ds_read_b128 v[218:221], v201 offset:7168
	global_load_lds_dwordx4 v[184:185], off
	v_lshl_add_u64 v[184:185], s[38:39], 0, v[166:167]
	s_add_i32 m0, s48, 0xe000
	s_nop 0
	global_load_lds_dwordx4 v[184:185], off
	s_waitcnt vmcnt(8)
	s_waitcnt lgkmcnt(0)
	s_barrier
	s_setprio 1
	v_mfma_f32_16x16x32_bf16 v[128:131], v[132:135], v[172:175], v[128:131]
	v_mfma_f32_16x16x32_bf16 v[124:127], v[140:143], v[172:175], v[124:127]
	v_mfma_f32_16x16x32_bf16 v[112:115], v[132:135], v[180:183], v[112:115]
	v_mfma_f32_16x16x32_bf16 v[108:111], v[140:143], v[180:183], v[108:111]
	v_mfma_f32_16x16x32_bf16 v[96:99], v[132:135], v[206:209], v[96:99]
	v_mfma_f32_16x16x32_bf16 v[92:95], v[140:143], v[206:209], v[92:95]
	v_mfma_f32_16x16x32_bf16 v[80:83], v[132:135], v[214:217], v[80:83]
	v_mfma_f32_16x16x32_bf16 v[76:79], v[140:143], v[214:217], v[76:79]
	v_mfma_f32_16x16x32_bf16 v[128:131], v[136:139], v[176:179], v[128:131]
	v_mfma_f32_16x16x32_bf16 v[124:127], v[144:147], v[176:179], v[124:127]
	v_mfma_f32_16x16x32_bf16 v[112:115], v[136:139], v[202:205], v[112:115]
	v_mfma_f32_16x16x32_bf16 v[108:111], v[144:147], v[202:205], v[108:111]
	v_mfma_f32_16x16x32_bf16 v[96:99], v[136:139], v[210:213], v[96:99]
	v_mfma_f32_16x16x32_bf16 v[92:95], v[144:147], v[210:213], v[92:95]
	v_mfma_f32_16x16x32_bf16 v[80:83], v[136:139], v[218:221], v[80:83]
	v_mfma_f32_16x16x32_bf16 v[76:79], v[144:147], v[218:221], v[76:79]
	v_mfma_f32_16x16x32_bf16 v[120:123], v[148:151], v[172:175], v[120:123]
	v_mfma_f32_16x16x32_bf16 v[116:119], v[156:159], v[172:175], v[116:119]
	v_mfma_f32_16x16x32_bf16 v[104:107], v[148:151], v[180:183], v[104:107]
	v_mfma_f32_16x16x32_bf16 v[100:103], v[156:159], v[180:183], v[100:103]
	v_mfma_f32_16x16x32_bf16 v[88:91], v[148:151], v[206:209], v[88:91]
	v_mfma_f32_16x16x32_bf16 v[84:87], v[156:159], v[206:209], v[84:87]
	v_mfma_f32_16x16x32_bf16 v[72:75], v[148:151], v[214:217], v[72:75]
	v_mfma_f32_16x16x32_bf16 v[68:71], v[156:159], v[214:217], v[68:71]
	v_mfma_f32_16x16x32_bf16 v[120:123], v[152:155], v[176:179], v[120:123]
	v_mfma_f32_16x16x32_bf16 v[116:119], v[168:171], v[176:179], v[116:119]
	v_mfma_f32_16x16x32_bf16 v[104:107], v[152:155], v[202:205], v[104:107]
	v_mfma_f32_16x16x32_bf16 v[100:103], v[168:171], v[202:205], v[100:103]
	v_mfma_f32_16x16x32_bf16 v[88:91], v[152:155], v[210:213], v[88:91]
	v_mfma_f32_16x16x32_bf16 v[84:87], v[168:171], v[210:213], v[84:87]
	v_mfma_f32_16x16x32_bf16 v[72:75], v[152:155], v[218:221], v[72:75]
	v_mfma_f32_16x16x32_bf16 v[68:71], v[168:171], v[218:221], v[68:71]
	s_setprio 0
	s_barrier
	s_add_i32 s65, s65, s45
	v_lshl_add_u64 v[184:185], s[62:63], 0, v[2:3]
	s_mov_b32 m0, s65
	ds_read_b128 v[172:175], v201 offset:16384
	ds_read_b128 v[176:179], v201 offset:17408
	ds_read_b128 v[180:183], v201 offset:18432
	ds_read_b128 v[202:205], v201 offset:19456
	ds_read_b128 v[206:209], v201 offset:20480
	ds_read_b128 v[210:213], v201 offset:21504
	ds_read_b128 v[214:217], v201 offset:22528
	ds_read_b128 v[218:221], v201 offset:23552
	global_load_lds_dwordx4 v[184:185], off
	s_add_i32 m0, s65, 0x2000
	v_lshl_add_u64 v[186:187], s[62:63], 0, v[162:163]
	s_add_u32 s62, s62, s24
	s_addc_u32 s63, s63, 0
	s_add_i32 s51, s51, s45
	global_load_lds_dwordx4 v[186:187], off
	v_lshl_add_u64 v[192:193], s[62:63], 0, v[2:3]
	s_mov_b32 m0, s51
	v_lshl_add_u64 v[194:195], s[62:63], 0, v[162:163]
	global_load_lds_dwordx4 v[192:193], off
	s_add_i32 m0, s51, 0x2000
	v_lshl_add_u64 v[196:197], s[40:41], 0, v[0:1]
	global_load_lds_dwordx4 v[194:195], off
	s_mov_b32 m0, s48
	v_lshl_add_u64 v[222:223], s[40:41], 0, v[160:161]
	global_load_lds_dwordx4 v[196:197], off
	s_mov_b32 m0, s49
	s_nop 0
	global_load_lds_dwordx4 v[222:223], off
	s_waitcnt vmcnt(8)
	s_waitcnt lgkmcnt(0)
	s_barrier
	s_setprio 1
	v_mfma_f32_16x16x32_bf16 v[64:67], v[132:135], v[172:175], v[64:67]
	v_mfma_f32_16x16x32_bf16 v[60:63], v[140:143], v[172:175], v[60:63]
	v_mfma_f32_16x16x32_bf16 v[48:51], v[132:135], v[180:183], v[48:51]
	v_mfma_f32_16x16x32_bf16 v[44:47], v[140:143], v[180:183], v[44:47]
	v_mfma_f32_16x16x32_bf16 v[32:35], v[132:135], v[206:209], v[32:35]
	v_mfma_f32_16x16x32_bf16 v[28:31], v[140:143], v[206:209], v[28:31]
	v_mfma_f32_16x16x32_bf16 v[16:19], v[132:135], v[214:217], v[16:19]
	v_mfma_f32_16x16x32_bf16 v[12:15], v[140:143], v[214:217], v[12:15]
	v_mfma_f32_16x16x32_bf16 v[64:67], v[136:139], v[176:179], v[64:67]
	v_mfma_f32_16x16x32_bf16 v[60:63], v[144:147], v[176:179], v[60:63]
	v_mfma_f32_16x16x32_bf16 v[48:51], v[136:139], v[202:205], v[48:51]
	v_mfma_f32_16x16x32_bf16 v[44:47], v[144:147], v[202:205], v[44:47]
	v_mfma_f32_16x16x32_bf16 v[32:35], v[136:139], v[210:213], v[32:35]
	v_mfma_f32_16x16x32_bf16 v[28:31], v[144:147], v[210:213], v[28:31]
	v_mfma_f32_16x16x32_bf16 v[16:19], v[136:139], v[218:221], v[16:19]
	v_mfma_f32_16x16x32_bf16 v[12:15], v[144:147], v[218:221], v[12:15]
	v_mfma_f32_16x16x32_bf16 v[56:59], v[148:151], v[172:175], v[56:59]
	v_mfma_f32_16x16x32_bf16 v[52:55], v[156:159], v[172:175], v[52:55]
	v_mfma_f32_16x16x32_bf16 v[40:43], v[148:151], v[180:183], v[40:43]
	v_mfma_f32_16x16x32_bf16 v[36:39], v[156:159], v[180:183], v[36:39]
	v_mfma_f32_16x16x32_bf16 v[24:27], v[148:151], v[206:209], v[24:27]
	v_mfma_f32_16x16x32_bf16 v[20:23], v[156:159], v[206:209], v[20:23]
	v_mfma_f32_16x16x32_bf16 v[8:11], v[148:151], v[214:217], v[8:11]
	v_mfma_f32_16x16x32_bf16 v[4:7], v[156:159], v[214:217], v[4:7]
	v_mfma_f32_16x16x32_bf16 v[56:59], v[152:155], v[176:179], v[56:59]
	v_mfma_f32_16x16x32_bf16 v[52:55], v[168:171], v[176:179], v[52:55]
	v_mfma_f32_16x16x32_bf16 v[40:43], v[152:155], v[202:205], v[40:43]
	v_mfma_f32_16x16x32_bf16 v[36:39], v[168:171], v[202:205], v[36:39]
	v_mfma_f32_16x16x32_bf16 v[24:27], v[152:155], v[210:213], v[24:27]
	v_mfma_f32_16x16x32_bf16 v[20:23], v[168:171], v[210:213], v[20:23]
	v_mfma_f32_16x16x32_bf16 v[8:11], v[152:155], v[218:221], v[8:11]
	v_mfma_f32_16x16x32_bf16 v[4:7], v[168:171], v[218:221], v[4:7]
	s_setprio 0
	s_barrier
	s_add_i32 s51, 0, 0x18000
	s_add_i32 s62, 0, 0x1c000
	v_add_u32_e32 v144, s51, v200
	v_add_u32_e32 v168, s62, v200
	ds_read_b128 v[132:135], v144
	ds_read_b128 v[136:139], v144 offset:1024
	ds_read_b128 v[140:143], v144 offset:2048
	ds_read_b128 v[144:147], v144 offset:3072
	ds_read_b128 v[148:151], v168
	ds_read_b128 v[152:155], v168 offset:1024
	ds_read_b128 v[156:159], v168 offset:2048
	ds_read_b128 v[168:171], v168 offset:3072
	s_add_u32 s40, s40, s24
	s_addc_u32 s41, s41, 0
	s_mov_b32 m0, s52
	v_lshl_add_u64 v[224:225], s[40:41], 0, v[0:1]
	ds_read_b128 v[172:175], v201 offset:32768
	ds_read_b128 v[176:179], v201 offset:33792
	ds_read_b128 v[180:183], v201 offset:34816
	ds_read_b128 v[202:205], v201 offset:35840
	ds_read_b128 v[206:209], v201 offset:36864
	ds_read_b128 v[210:213], v201 offset:37888
	ds_read_b128 v[214:217], v201 offset:38912
	ds_read_b128 v[218:221], v201 offset:39936
	global_load_lds_dwordx4 v[224:225], off
	v_lshl_add_u64 v[224:225], s[40:41], 0, v[160:161]
	s_mov_b32 m0, s53
	s_nop 0
	global_load_lds_dwordx4 v[224:225], off
	s_waitcnt vmcnt(8)
	s_waitcnt lgkmcnt(0)
	s_barrier
	s_setprio 1
	v_mfma_f32_16x16x32_bf16 v[128:131], v[132:135], v[172:175], v[128:131]
	v_mfma_f32_16x16x32_bf16 v[124:127], v[140:143], v[172:175], v[124:127]
	v_mfma_f32_16x16x32_bf16 v[112:115], v[132:135], v[180:183], v[112:115]
	v_mfma_f32_16x16x32_bf16 v[108:111], v[140:143], v[180:183], v[108:111]
	v_mfma_f32_16x16x32_bf16 v[96:99], v[132:135], v[206:209], v[96:99]
	v_mfma_f32_16x16x32_bf16 v[92:95], v[140:143], v[206:209], v[92:95]
	v_mfma_f32_16x16x32_bf16 v[80:83], v[132:135], v[214:217], v[80:83]
	v_mfma_f32_16x16x32_bf16 v[76:79], v[140:143], v[214:217], v[76:79]
	v_mfma_f32_16x16x32_bf16 v[128:131], v[136:139], v[176:179], v[128:131]
	v_mfma_f32_16x16x32_bf16 v[124:127], v[144:147], v[176:179], v[124:127]
	v_mfma_f32_16x16x32_bf16 v[112:115], v[136:139], v[202:205], v[112:115]
	v_mfma_f32_16x16x32_bf16 v[108:111], v[144:147], v[202:205], v[108:111]
	v_mfma_f32_16x16x32_bf16 v[96:99], v[136:139], v[210:213], v[96:99]
	v_mfma_f32_16x16x32_bf16 v[92:95], v[144:147], v[210:213], v[92:95]
	v_mfma_f32_16x16x32_bf16 v[80:83], v[136:139], v[218:221], v[80:83]
	v_mfma_f32_16x16x32_bf16 v[76:79], v[144:147], v[218:221], v[76:79]
	v_mfma_f32_16x16x32_bf16 v[120:123], v[148:151], v[172:175], v[120:123]
	v_mfma_f32_16x16x32_bf16 v[116:119], v[156:159], v[172:175], v[116:119]
	v_mfma_f32_16x16x32_bf16 v[104:107], v[148:151], v[180:183], v[104:107]
	v_mfma_f32_16x16x32_bf16 v[100:103], v[156:159], v[180:183], v[100:103]
	v_mfma_f32_16x16x32_bf16 v[88:91], v[148:151], v[206:209], v[88:91]
	v_mfma_f32_16x16x32_bf16 v[84:87], v[156:159], v[206:209], v[84:87]
	v_mfma_f32_16x16x32_bf16 v[72:75], v[148:151], v[214:217], v[72:75]
	v_mfma_f32_16x16x32_bf16 v[68:71], v[156:159], v[214:217], v[68:71]
	v_mfma_f32_16x16x32_bf16 v[120:123], v[152:155], v[176:179], v[120:123]
	v_mfma_f32_16x16x32_bf16 v[116:119], v[168:171], v[176:179], v[116:119]
	v_mfma_f32_16x16x32_bf16 v[104:107], v[152:155], v[202:205], v[104:107]
	v_mfma_f32_16x16x32_bf16 v[100:103], v[168:171], v[202:205], v[100:103]
	v_mfma_f32_16x16x32_bf16 v[88:91], v[152:155], v[210:213], v[88:91]
	v_mfma_f32_16x16x32_bf16 v[84:87], v[168:171], v[210:213], v[84:87]
	v_mfma_f32_16x16x32_bf16 v[72:75], v[152:155], v[218:221], v[72:75]
	v_mfma_f32_16x16x32_bf16 v[68:71], v[168:171], v[218:221], v[68:71]
	s_setprio 0
	s_barrier
	s_add_i32 s40, s51, s45
	v_lshl_add_u64 v[184:185], v[184:185], 0, s[46:47]
	s_mov_b32 m0, s40
	ds_read_b128 v[172:175], v201 offset:49152
	ds_read_b128 v[176:179], v201 offset:50176
	ds_read_b128 v[180:183], v201 offset:51200
	ds_read_b128 v[202:205], v201 offset:52224
	ds_read_b128 v[206:209], v201 offset:53248
	ds_read_b128 v[210:213], v201 offset:54272
	ds_read_b128 v[214:217], v201 offset:55296
	ds_read_b128 v[218:221], v201 offset:56320
	global_load_lds_dwordx4 v[184:185], off
	v_lshl_add_u64 v[184:185], v[186:187], 0, s[46:47]
	s_add_i32 m0, s40, 0x2000
	s_add_i32 s40, s62, s45
	global_load_lds_dwordx4 v[184:185], off
	v_lshl_add_u64 v[184:185], v[192:193], 0, s[46:47]
	s_mov_b32 m0, s40
	s_nop 0
	global_load_lds_dwordx4 v[184:185], off
	v_lshl_add_u64 v[184:185], v[194:195], 0, s[46:47]
	s_add_i32 m0, s40, 0x2000
	s_nop 0
	global_load_lds_dwordx4 v[184:185], off
	v_lshl_add_u64 v[184:185], v[196:197], 0, s[46:47]
	s_mov_b32 m0, s71
	s_nop 0
	global_load_lds_dwordx4 v[184:185], off
	v_lshl_add_u64 v[184:185], v[222:223], 0, s[46:47]
	s_mov_b32 m0, s72
	s_nop 0
	global_load_lds_dwordx4 v[184:185], off
	s_waitcnt vmcnt(8)
	s_waitcnt lgkmcnt(0)
	s_barrier
	s_setprio 1
	v_mfma_f32_16x16x32_bf16 v[64:67], v[132:135], v[172:175], v[64:67]
	v_mfma_f32_16x16x32_bf16 v[60:63], v[140:143], v[172:175], v[60:63]
	v_mfma_f32_16x16x32_bf16 v[48:51], v[132:135], v[180:183], v[48:51]
	v_mfma_f32_16x16x32_bf16 v[44:47], v[140:143], v[180:183], v[44:47]
	v_mfma_f32_16x16x32_bf16 v[32:35], v[132:135], v[206:209], v[32:35]
	v_mfma_f32_16x16x32_bf16 v[28:31], v[140:143], v[206:209], v[28:31]
	v_mfma_f32_16x16x32_bf16 v[16:19], v[132:135], v[214:217], v[16:19]
	v_mfma_f32_16x16x32_bf16 v[12:15], v[140:143], v[214:217], v[12:15]
	v_mfma_f32_16x16x32_bf16 v[64:67], v[136:139], v[176:179], v[64:67]
	v_mfma_f32_16x16x32_bf16 v[60:63], v[144:147], v[176:179], v[60:63]
	v_mfma_f32_16x16x32_bf16 v[48:51], v[136:139], v[202:205], v[48:51]
	v_mfma_f32_16x16x32_bf16 v[44:47], v[144:147], v[202:205], v[44:47]
	v_mfma_f32_16x16x32_bf16 v[32:35], v[136:139], v[210:213], v[32:35]
	v_mfma_f32_16x16x32_bf16 v[28:31], v[144:147], v[210:213], v[28:31]
	v_mfma_f32_16x16x32_bf16 v[16:19], v[136:139], v[218:221], v[16:19]
	v_mfma_f32_16x16x32_bf16 v[12:15], v[144:147], v[218:221], v[12:15]
	v_mfma_f32_16x16x32_bf16 v[56:59], v[148:151], v[172:175], v[56:59]
	v_mfma_f32_16x16x32_bf16 v[52:55], v[156:159], v[172:175], v[52:55]
	v_mfma_f32_16x16x32_bf16 v[40:43], v[148:151], v[180:183], v[40:43]
	v_mfma_f32_16x16x32_bf16 v[36:39], v[156:159], v[180:183], v[36:39]
	v_mfma_f32_16x16x32_bf16 v[24:27], v[148:151], v[206:209], v[24:27]
	v_mfma_f32_16x16x32_bf16 v[20:23], v[156:159], v[206:209], v[20:23]
	v_mfma_f32_16x16x32_bf16 v[8:11], v[148:151], v[214:217], v[8:11]
	v_mfma_f32_16x16x32_bf16 v[4:7], v[156:159], v[214:217], v[4:7]
	v_mfma_f32_16x16x32_bf16 v[56:59], v[152:155], v[176:179], v[56:59]
	v_mfma_f32_16x16x32_bf16 v[52:55], v[168:171], v[176:179], v[52:55]
	v_mfma_f32_16x16x32_bf16 v[40:43], v[152:155], v[202:205], v[40:43]
	v_mfma_f32_16x16x32_bf16 v[36:39], v[168:171], v[202:205], v[36:39]
	v_mfma_f32_16x16x32_bf16 v[24:27], v[152:155], v[210:213], v[24:27]
	v_mfma_f32_16x16x32_bf16 v[20:23], v[168:171], v[210:213], v[20:23]
	v_mfma_f32_16x16x32_bf16 v[8:11], v[152:155], v[218:221], v[8:11]
	v_mfma_f32_16x16x32_bf16 v[4:7], v[168:171], v[218:221], v[4:7]
	s_setprio 0
	s_barrier
	s_add_u32 s38, s38, 0x100
	s_addc_u32 s39, s39, 0
	s_add_u32 s31, s31, 0x100
	s_addc_u32 s35, s35, 0
	s_cmp_ge_u32 s50, s70
	s_mov_b32 s40, s50
	s_cbranch_scc0 .LBB0_939
	s_and_b64 vcc, exec, s[26:27]
	s_cbranch_vccz .LBB0_942
	s_barrier
